# v16 plus DPP butterflies in the attention branch-combine and preloaded residual rows in the P3/P5 residual epilogues
# speedup vs baseline: 1.0165x; 1.0042x over previous
.LBB0_736:
	s_lshl_b32 s14, s14, 8
	v_mov_b32_e32 v166, v149
	v_mov_b32_e32 v167, v148
	s_add_i32 s14, s14, s61
	s_lshl_b32 s22, s12, 8
	v_add_u32_e32 v146, s14, v166
	s_or_b32 s22, s22, s62
	v_ashrrev_i32_e32 v147, 31, v146
	v_lshl_add_u32 v144, v167, 3, s22
	v_lshlrev_b64 v[154:155], 11, v[146:147]
	v_ashrrev_i32_e32 v145, 31, v144
	v_lshl_add_u64 v[154:155], s[18:19], 0, v[154:155]
	v_lshl_add_u64 v[158:159], v[144:145], 1, v[154:155]
	v_mov_b32_e32 v236, 0x8000
	v_mov_b32_e32 v237, 0
	v_mov_b32_e32 v238, 0x28000
	v_mov_b32_e32 v239, 0
	global_load_dwordx4 v[168:171], v[158:159], off
	global_load_dwordx4 v[172:175], v[158:159], off offset:256
	v_lshl_add_u64 v[234:235], v[158:159], 0, v[236:237]
	global_load_dwordx4 v[176:179], v[234:235], off
	global_load_dwordx4 v[180:183], v[234:235], off offset:256
	v_lshl_add_u64 v[234:235], v[234:235], 0, v[236:237]
	global_load_dwordx4 v[184:187], v[234:235], off
	global_load_dwordx4 v[188:191], v[234:235], off offset:256
	v_lshl_add_u64 v[234:235], v[234:235], 0, v[236:237]
	global_load_dwordx4 v[192:195], v[234:235], off
	global_load_dwordx4 v[196:199], v[234:235], off offset:256
	v_lshl_add_u64 v[234:235], v[234:235], 0, v[238:239]
	global_load_dwordx4 v[200:203], v[234:235], off
	global_load_dwordx4 v[204:207], v[234:235], off offset:256
	v_lshl_add_u64 v[234:235], v[234:235], 0, v[236:237]
	global_load_dwordx4 v[208:211], v[234:235], off
	global_load_dwordx4 v[212:215], v[234:235], off offset:256
	v_lshl_add_u64 v[234:235], v[234:235], 0, v[236:237]
	global_load_dwordx4 v[216:219], v[234:235], off
	global_load_dwordx4 v[220:223], v[234:235], off offset:256
	v_lshl_add_u64 v[234:235], v[234:235], 0, v[236:237]
	global_load_dwordx4 v[226:229], v[234:235], off
	global_load_dwordx4 v[230:233], v[234:235], off offset:256
	v_cmp_eq_u32_e32 vcc, 0, v167
	s_waitcnt vmcnt(15)
	v_mov_b32_e32 v154, v168
	v_mov_b32_e32 v155, v169
	v_mov_b32_e32 v156, v170
	v_mov_b32_e32 v157, v171
	v_lshlrev_b32_e32 v160, 16, v154
	v_and_b32_e32 v161, 0xffff0000, v154
	v_lshlrev_b32_e32 v154, 16, v155
	v_and_b32_e32 v155, 0xffff0000, v155
	v_lshlrev_b32_e32 v162, 16, v156
	v_and_b32_e32 v163, 0xffff0000, v156
	v_lshlrev_b32_e32 v156, 16, v157
	v_and_b32_e32 v157, 0xffff0000, v157
	v_pk_add_f32 v[126:127], v[126:127], v[154:155]
	v_pk_add_f32 v[160:161], v[124:125], v[160:161]
	v_pk_add_f32 v[164:165], v[122:123], v[156:157]
	v_pk_add_f32 v[162:163], v[120:121], v[162:163]
	v_cvt_pk_bf16_f32 v122, v160, v161
	v_cvt_pk_bf16_f32 v123, v126, v127
	v_mul_f32_e32 v161, v161, v161
	v_cvt_pk_bf16_f32 v124, v162, v163
	v_cvt_pk_bf16_f32 v125, v164, v165
	v_mul_f32_e32 v127, v127, v127
	v_mul_f32_e32 v163, v163, v163
	v_mul_f32_e32 v165, v165, v165
	v_fmac_f32_e32 v161, v160, v160
	v_fmac_f32_e32 v127, v126, v126
	v_fmac_f32_e32 v163, v162, v162
	v_fmac_f32_e32 v165, v164, v164
	v_add_f32_e32 v126, v161, v127
	v_add_f32_e32 v127, v163, v165
	v_add_f32_e32 v162, v126, v127
	v_lshlrev_b32_e32 v120, 2, v166
	v_lshl_add_u32 v121, v167, 6, v120
	v_xor_b32_e32 v120, 64, v121
	global_store_dwordx4 v[158:159], v[122:125], off
	s_waitcnt vmcnt(15)
	v_mov_b32_e32 v154, v172
	v_mov_b32_e32 v155, v173
	v_mov_b32_e32 v156, v174
	v_mov_b32_e32 v157, v175
	v_lshlrev_b32_e32 v126, 16, v154
	v_and_b32_e32 v127, 0xffff0000, v154
	v_lshlrev_b32_e32 v154, 16, v155
	v_and_b32_e32 v155, 0xffff0000, v155
	v_lshlrev_b32_e32 v160, 16, v156
	v_and_b32_e32 v161, 0xffff0000, v156
	v_lshlrev_b32_e32 v156, 16, v157
	v_and_b32_e32 v157, 0xffff0000, v157
	v_pk_add_f32 v[118:119], v[118:119], v[154:155]
	v_pk_add_f32 v[116:117], v[116:117], v[126:127]
	v_pk_add_f32 v[126:127], v[114:115], v[156:157]
	v_pk_add_f32 v[154:155], v[112:113], v[160:161]
	v_mul_f32_e32 v112, v117, v117
	v_mul_f32_e32 v113, v119, v119
	v_mul_f32_e32 v114, v155, v155
	v_mul_f32_e32 v115, v127, v127
	v_fmac_f32_e32 v112, v116, v116
	v_fmac_f32_e32 v113, v118, v118
	v_fmac_f32_e32 v114, v154, v154
	v_fmac_f32_e32 v115, v126, v126
	v_add_f32_e32 v112, v112, v113
	v_add_f32_e32 v113, v114, v115
	v_add_f32_e32 v112, v112, v113
	v_add_f32_e32 v112, v162, v112
	ds_bpermute_b32 v113, v120, v112
	v_xor_b32_e32 v114, 0x80, v121
	v_cvt_pk_bf16_f32 v116, v116, v117
	v_cvt_pk_bf16_f32 v117, v118, v119
	v_cvt_pk_bf16_f32 v118, v154, v155
	s_waitcnt lgkmcnt(0)
	v_add_f32_e32 v112, v112, v113
	ds_bpermute_b32 v113, v114, v112
	v_cvt_pk_bf16_f32 v119, v126, v127
	global_store_dwordx4 v[158:159], v[116:119], off offset:256
	s_and_saveexec_b64 s[46:47], vcc
	s_cbranch_execz .LBB0_738
	s_waitcnt lgkmcnt(0)
	v_add_f32_e32 v115, v112, v113
	s_lshl_b32 s26, s12, 2
	v_lshlrev_b64 v[112:113], 6, v[146:147]
	s_ashr_i32 s27, s26, 31
	v_lshl_add_u64 v[112:113], s[10:11], 0, v[112:113]
	v_lshl_add_u64 v[112:113], s[26:27], 2, v[112:113]
	s_lshl_b32 s14, s60, 2
	v_lshl_add_u64 v[112:113], v[112:113], 0, s[14:15]
	global_store_dword v[112:113], v115, off
.LBB0_738:
	s_or_b64 exec, exec, s[46:47]
	v_add_u32_e32 v112, 16, v146
	s_waitcnt lgkmcnt(0)
	v_ashrrev_i32_e32 v113, 31, v112
	v_lshlrev_b64 v[116:117], 11, v[112:113]
	v_lshl_add_u64 v[116:117], s[18:19], 0, v[116:117]
	v_lshl_add_u64 v[122:123], v[144:145], 1, v[116:117]
	s_waitcnt vmcnt(16)
	v_mov_b32_e32 v116, v176
	v_mov_b32_e32 v117, v177
	v_mov_b32_e32 v118, v178
	v_mov_b32_e32 v119, v179
	v_lshlrev_b32_e32 v124, 16, v116
	v_and_b32_e32 v125, 0xffff0000, v116
	v_lshlrev_b32_e32 v116, 16, v117
	v_and_b32_e32 v117, 0xffff0000, v117
	v_lshlrev_b32_e32 v126, 16, v118
	v_and_b32_e32 v127, 0xffff0000, v118
	v_lshlrev_b32_e32 v118, 16, v119
	v_and_b32_e32 v119, 0xffff0000, v119
	v_pk_add_f32 v[116:117], v[110:111], v[116:117]
	v_pk_add_f32 v[124:125], v[108:109], v[124:125]
	v_pk_add_f32 v[118:119], v[106:107], v[118:119]
	v_pk_add_f32 v[126:127], v[104:105], v[126:127]
	v_cvt_pk_bf16_f32 v104, v124, v125
	v_cvt_pk_bf16_f32 v105, v116, v117
	v_mul_f32_e32 v115, v125, v125
	v_cvt_pk_bf16_f32 v106, v126, v127
	v_cvt_pk_bf16_f32 v107, v118, v119
	v_mul_f32_e32 v117, v117, v117
	v_mul_f32_e32 v121, v127, v127
	v_mul_f32_e32 v119, v119, v119
	v_fmac_f32_e32 v115, v124, v124
	v_fmac_f32_e32 v117, v116, v116
	v_fmac_f32_e32 v121, v126, v126
	v_fmac_f32_e32 v119, v118, v118
	v_add_f32_e32 v115, v115, v117
	v_add_f32_e32 v116, v121, v119
	v_add_f32_e32 v115, v115, v116
	global_store_dwordx4 v[122:123], v[104:107], off
	s_waitcnt vmcnt(16)
	v_mov_b32_e32 v108, v180
	v_mov_b32_e32 v109, v181
	v_mov_b32_e32 v110, v182
	v_mov_b32_e32 v111, v183
	v_lshlrev_b32_e32 v116, 16, v108
	v_and_b32_e32 v117, 0xffff0000, v108
	v_lshlrev_b32_e32 v108, 16, v109
	v_and_b32_e32 v109, 0xffff0000, v109
	v_lshlrev_b32_e32 v118, 16, v110
	v_and_b32_e32 v119, 0xffff0000, v110
	v_lshlrev_b32_e32 v110, 16, v111
	v_and_b32_e32 v111, 0xffff0000, v111
	v_pk_add_f32 v[102:103], v[102:103], v[108:109]
	v_pk_add_f32 v[100:101], v[100:101], v[116:117]
	v_pk_add_f32 v[108:109], v[98:99], v[110:111]
	v_pk_add_f32 v[110:111], v[96:97], v[118:119]
	v_mul_f32_e32 v96, v101, v101
	v_mul_f32_e32 v97, v103, v103
	v_mul_f32_e32 v98, v111, v111
	v_mul_f32_e32 v99, v109, v109
	v_fmac_f32_e32 v96, v100, v100
	v_fmac_f32_e32 v97, v102, v102
	v_fmac_f32_e32 v98, v110, v110
	v_fmac_f32_e32 v99, v108, v108
	v_add_f32_e32 v96, v96, v97
	v_add_f32_e32 v97, v98, v99
	v_add_f32_e32 v96, v96, v97
	v_add_f32_e32 v96, v115, v96
	ds_bpermute_b32 v97, v120, v96
	v_cvt_pk_bf16_f32 v98, v100, v101
	v_cvt_pk_bf16_f32 v99, v102, v103
	v_cvt_pk_bf16_f32 v100, v110, v111
	v_cvt_pk_bf16_f32 v101, v108, v109
	s_waitcnt lgkmcnt(0)
	v_add_f32_e32 v96, v96, v97
	ds_bpermute_b32 v97, v114, v96
	global_store_dwordx4 v[122:123], v[98:101], off offset:256
	s_and_saveexec_b64 s[46:47], vcc
	s_cbranch_execz .LBB0_740
	s_waitcnt lgkmcnt(0)
	v_add_f32_e32 v98, v96, v97
	s_lshl_b32 s26, s12, 2
	v_lshlrev_b64 v[96:97], 6, v[112:113]
	s_ashr_i32 s27, s26, 31
	v_lshl_add_u64 v[96:97], s[10:11], 0, v[96:97]
	v_lshl_add_u64 v[96:97], s[26:27], 2, v[96:97]
	s_lshl_b32 s14, s60, 2
	v_lshl_add_u64 v[96:97], v[96:97], 0, s[14:15]
	global_store_dword v[96:97], v98, off
.LBB0_740:
	s_or_b64 exec, exec, s[46:47]
	v_add_u32_e32 v96, 32, v146
	s_waitcnt lgkmcnt(0)
	v_ashrrev_i32_e32 v97, 31, v96
	v_lshlrev_b64 v[98:99], 11, v[96:97]
	v_lshl_add_u64 v[98:99], s[18:19], 0, v[98:99]
	v_lshl_add_u64 v[102:103], v[144:145], 1, v[98:99]
	s_waitcnt vmcnt(17)
	v_mov_b32_e32 v98, v184
	v_mov_b32_e32 v99, v185
	v_mov_b32_e32 v100, v186
	v_mov_b32_e32 v101, v187
	v_lshlrev_b32_e32 v104, 16, v98
	v_and_b32_e32 v105, 0xffff0000, v98
	v_lshlrev_b32_e32 v98, 16, v99
	v_and_b32_e32 v99, 0xffff0000, v99
	v_lshlrev_b32_e32 v106, 16, v100
	v_and_b32_e32 v107, 0xffff0000, v100
	v_lshlrev_b32_e32 v100, 16, v101
	v_and_b32_e32 v101, 0xffff0000, v101
	v_pk_add_f32 v[98:99], v[94:95], v[98:99]
	v_pk_add_f32 v[104:105], v[92:93], v[104:105]
	v_pk_add_f32 v[100:101], v[90:91], v[100:101]
	v_pk_add_f32 v[106:107], v[88:89], v[106:107]
	v_cvt_pk_bf16_f32 v88, v104, v105
	v_cvt_pk_bf16_f32 v89, v98, v99
	v_mul_f32_e32 v105, v105, v105
	v_cvt_pk_bf16_f32 v90, v106, v107
	v_cvt_pk_bf16_f32 v91, v100, v101
	v_mul_f32_e32 v99, v99, v99
	v_mul_f32_e32 v107, v107, v107
	v_mul_f32_e32 v101, v101, v101
	v_fmac_f32_e32 v105, v104, v104
	v_fmac_f32_e32 v99, v98, v98
	v_fmac_f32_e32 v107, v106, v106
	v_fmac_f32_e32 v101, v100, v100
	v_add_f32_e32 v98, v105, v99
	v_add_f32_e32 v99, v107, v101
	v_add_f32_e32 v104, v98, v99
	global_store_dwordx4 v[102:103], v[88:91], off
	s_waitcnt vmcnt(17)
	v_mov_b32_e32 v92, v188
	v_mov_b32_e32 v93, v189
	v_mov_b32_e32 v94, v190
	v_mov_b32_e32 v95, v191
	v_lshlrev_b32_e32 v98, 16, v92
	v_and_b32_e32 v99, 0xffff0000, v92
	v_lshlrev_b32_e32 v92, 16, v93
	v_and_b32_e32 v93, 0xffff0000, v93
	v_lshlrev_b32_e32 v100, 16, v94
	v_and_b32_e32 v101, 0xffff0000, v94
	v_lshlrev_b32_e32 v94, 16, v95
	v_and_b32_e32 v95, 0xffff0000, v95
	v_pk_add_f32 v[86:87], v[86:87], v[92:93]
	v_pk_add_f32 v[84:85], v[84:85], v[98:99]
	v_pk_add_f32 v[92:93], v[82:83], v[94:95]
	v_pk_add_f32 v[94:95], v[80:81], v[100:101]
	v_mul_f32_e32 v80, v85, v85
	v_mul_f32_e32 v81, v87, v87
	v_mul_f32_e32 v82, v95, v95
	v_mul_f32_e32 v83, v93, v93
	v_fmac_f32_e32 v80, v84, v84
	v_fmac_f32_e32 v81, v86, v86
	v_fmac_f32_e32 v82, v94, v94
	v_fmac_f32_e32 v83, v92, v92
	v_add_f32_e32 v80, v80, v81
	v_add_f32_e32 v81, v82, v83
	v_add_f32_e32 v80, v80, v81
	v_add_f32_e32 v80, v104, v80
	ds_bpermute_b32 v81, v120, v80
	v_cvt_pk_bf16_f32 v82, v84, v85
	v_cvt_pk_bf16_f32 v83, v86, v87
	v_cvt_pk_bf16_f32 v84, v94, v95
	v_cvt_pk_bf16_f32 v85, v92, v93
	s_waitcnt lgkmcnt(0)
	v_add_f32_e32 v80, v80, v81
	ds_bpermute_b32 v81, v114, v80
	global_store_dwordx4 v[102:103], v[82:85], off offset:256
	s_and_saveexec_b64 s[46:47], vcc
	s_cbranch_execz .LBB0_742
	s_waitcnt lgkmcnt(0)
	v_add_f32_e32 v82, v80, v81
	s_lshl_b32 s26, s12, 2
	v_lshlrev_b64 v[80:81], 6, v[96:97]
	s_ashr_i32 s27, s26, 31
	v_lshl_add_u64 v[80:81], s[10:11], 0, v[80:81]
	v_lshl_add_u64 v[80:81], s[26:27], 2, v[80:81]
	s_lshl_b32 s14, s60, 2
	v_lshl_add_u64 v[80:81], v[80:81], 0, s[14:15]
	global_store_dword v[80:81], v82, off
.LBB0_742:
	s_or_b64 exec, exec, s[46:47]
	v_add_u32_e32 v80, 48, v146
	s_waitcnt lgkmcnt(0)
	v_ashrrev_i32_e32 v81, 31, v80
	v_lshlrev_b64 v[82:83], 11, v[80:81]
	v_lshl_add_u64 v[82:83], s[18:19], 0, v[82:83]
	v_lshl_add_u64 v[86:87], v[144:145], 1, v[82:83]
	s_waitcnt vmcnt(18)
	v_mov_b32_e32 v82, v192
	v_mov_b32_e32 v83, v193
	v_mov_b32_e32 v84, v194
	v_mov_b32_e32 v85, v195
	v_lshlrev_b32_e32 v88, 16, v82
	v_and_b32_e32 v89, 0xffff0000, v82
	v_lshlrev_b32_e32 v82, 16, v83
	v_and_b32_e32 v83, 0xffff0000, v83
	v_lshlrev_b32_e32 v90, 16, v84
	v_and_b32_e32 v91, 0xffff0000, v84
	v_lshlrev_b32_e32 v84, 16, v85
	v_and_b32_e32 v85, 0xffff0000, v85
	v_pk_add_f32 v[82:83], v[78:79], v[82:83]
	v_pk_add_f32 v[88:89], v[76:77], v[88:89]
	v_pk_add_f32 v[84:85], v[74:75], v[84:85]
	v_pk_add_f32 v[90:91], v[72:73], v[90:91]
	v_cvt_pk_bf16_f32 v72, v88, v89
	v_cvt_pk_bf16_f32 v73, v82, v83
	v_mul_f32_e32 v89, v89, v89
	v_cvt_pk_bf16_f32 v74, v90, v91
	v_cvt_pk_bf16_f32 v75, v84, v85
	v_mul_f32_e32 v83, v83, v83
	v_mul_f32_e32 v91, v91, v91
	v_mul_f32_e32 v85, v85, v85
	v_fmac_f32_e32 v89, v88, v88
	v_fmac_f32_e32 v83, v82, v82
	v_fmac_f32_e32 v91, v90, v90
	v_fmac_f32_e32 v85, v84, v84
	v_add_f32_e32 v82, v89, v83
	v_add_f32_e32 v83, v91, v85
	v_add_f32_e32 v88, v82, v83
	global_store_dwordx4 v[86:87], v[72:75], off
	s_waitcnt vmcnt(18)
	v_mov_b32_e32 v76, v196
	v_mov_b32_e32 v77, v197
	v_mov_b32_e32 v78, v198
	v_mov_b32_e32 v79, v199
	v_lshlrev_b32_e32 v82, 16, v76
	v_and_b32_e32 v83, 0xffff0000, v76
	v_lshlrev_b32_e32 v76, 16, v77
	v_and_b32_e32 v77, 0xffff0000, v77
	v_lshlrev_b32_e32 v84, 16, v78
	v_and_b32_e32 v85, 0xffff0000, v78
	v_lshlrev_b32_e32 v78, 16, v79
	v_and_b32_e32 v79, 0xffff0000, v79
	v_pk_add_f32 v[70:71], v[70:71], v[76:77]
	v_pk_add_f32 v[68:69], v[68:69], v[82:83]
	v_pk_add_f32 v[76:77], v[66:67], v[78:79]
	v_pk_add_f32 v[78:79], v[64:65], v[84:85]
	v_mul_f32_e32 v64, v69, v69
	v_mul_f32_e32 v65, v71, v71
	v_mul_f32_e32 v66, v79, v79
	v_mul_f32_e32 v67, v77, v77
	v_fmac_f32_e32 v64, v68, v68
	v_fmac_f32_e32 v65, v70, v70
	v_fmac_f32_e32 v66, v78, v78
	v_fmac_f32_e32 v67, v76, v76
	v_add_f32_e32 v64, v64, v65
	v_add_f32_e32 v65, v66, v67
	v_add_f32_e32 v64, v64, v65
	v_add_f32_e32 v64, v88, v64
	ds_bpermute_b32 v65, v120, v64
	v_cvt_pk_bf16_f32 v66, v68, v69
	v_cvt_pk_bf16_f32 v67, v70, v71
	v_cvt_pk_bf16_f32 v68, v78, v79
	v_cvt_pk_bf16_f32 v69, v76, v77
	s_waitcnt lgkmcnt(0)
	v_add_f32_e32 v64, v64, v65
	ds_bpermute_b32 v65, v114, v64
	global_store_dwordx4 v[86:87], v[66:69], off offset:256
	s_and_saveexec_b64 s[46:47], vcc
	s_cbranch_execz .LBB0_744
	s_waitcnt lgkmcnt(0)
	v_add_f32_e32 v66, v64, v65
	s_lshl_b32 s26, s12, 2
	v_lshlrev_b64 v[64:65], 6, v[80:81]
	s_ashr_i32 s27, s26, 31
	v_lshl_add_u64 v[64:65], s[10:11], 0, v[64:65]
	v_lshl_add_u64 v[64:65], s[26:27], 2, v[64:65]
	s_lshl_b32 s14, s60, 2
	v_lshl_add_u64 v[64:65], v[64:65], 0, s[14:15]
	global_store_dword v[64:65], v66, off
.LBB0_744:
	s_or_b64 exec, exec, s[46:47]
	v_add_u32_e32 v64, 0x80, v146
	s_waitcnt lgkmcnt(0)
	v_ashrrev_i32_e32 v65, 31, v64
	v_lshlrev_b64 v[66:67], 11, v[64:65]
	v_lshl_add_u64 v[66:67], s[18:19], 0, v[66:67]
	v_lshl_add_u64 v[70:71], v[144:145], 1, v[66:67]
	s_waitcnt vmcnt(19)
	v_mov_b32_e32 v66, v200
	v_mov_b32_e32 v67, v201
	v_mov_b32_e32 v68, v202
	v_mov_b32_e32 v69, v203
	v_lshlrev_b32_e32 v72, 16, v66
	v_and_b32_e32 v73, 0xffff0000, v66
	v_lshlrev_b32_e32 v66, 16, v67
	v_and_b32_e32 v67, 0xffff0000, v67
	v_lshlrev_b32_e32 v74, 16, v68
	v_and_b32_e32 v75, 0xffff0000, v68
	v_lshlrev_b32_e32 v68, 16, v69
	v_and_b32_e32 v69, 0xffff0000, v69
	v_pk_add_f32 v[66:67], v[62:63], v[66:67]
	v_pk_add_f32 v[72:73], v[60:61], v[72:73]
	v_pk_add_f32 v[68:69], v[58:59], v[68:69]
	v_pk_add_f32 v[74:75], v[56:57], v[74:75]
	v_cvt_pk_bf16_f32 v56, v72, v73
	v_cvt_pk_bf16_f32 v57, v66, v67
	v_mul_f32_e32 v73, v73, v73
	v_cvt_pk_bf16_f32 v58, v74, v75
	v_cvt_pk_bf16_f32 v59, v68, v69
	v_mul_f32_e32 v67, v67, v67
	v_mul_f32_e32 v75, v75, v75
	v_mul_f32_e32 v69, v69, v69
	v_fmac_f32_e32 v73, v72, v72
	v_fmac_f32_e32 v67, v66, v66
	v_fmac_f32_e32 v75, v74, v74
	v_fmac_f32_e32 v69, v68, v68
	v_add_f32_e32 v66, v73, v67
	v_add_f32_e32 v67, v75, v69
	v_add_f32_e32 v72, v66, v67
	global_store_dwordx4 v[70:71], v[56:59], off
	s_waitcnt vmcnt(19)
	v_mov_b32_e32 v60, v204
	v_mov_b32_e32 v61, v205
	v_mov_b32_e32 v62, v206
	v_mov_b32_e32 v63, v207
	v_lshlrev_b32_e32 v66, 16, v60
	v_and_b32_e32 v67, 0xffff0000, v60
	v_lshlrev_b32_e32 v60, 16, v61
	v_and_b32_e32 v61, 0xffff0000, v61
	v_lshlrev_b32_e32 v68, 16, v62
	v_and_b32_e32 v69, 0xffff0000, v62
	v_lshlrev_b32_e32 v62, 16, v63
	v_and_b32_e32 v63, 0xffff0000, v63
	v_pk_add_f32 v[54:55], v[54:55], v[60:61]
	v_pk_add_f32 v[52:53], v[52:53], v[66:67]
	v_pk_add_f32 v[60:61], v[50:51], v[62:63]
	v_pk_add_f32 v[62:63], v[48:49], v[68:69]
	v_mul_f32_e32 v48, v53, v53
	v_mul_f32_e32 v49, v55, v55
	v_mul_f32_e32 v50, v63, v63
	v_mul_f32_e32 v51, v61, v61
	v_fmac_f32_e32 v48, v52, v52
	v_fmac_f32_e32 v49, v54, v54
	v_fmac_f32_e32 v50, v62, v62
	v_fmac_f32_e32 v51, v60, v60
	v_add_f32_e32 v48, v48, v49
	v_add_f32_e32 v49, v50, v51
	v_add_f32_e32 v48, v48, v49
	v_add_f32_e32 v48, v72, v48
	ds_bpermute_b32 v49, v120, v48
	v_cvt_pk_bf16_f32 v50, v52, v53
	v_cvt_pk_bf16_f32 v51, v54, v55
	v_cvt_pk_bf16_f32 v52, v62, v63
	v_cvt_pk_bf16_f32 v53, v60, v61
	s_waitcnt lgkmcnt(0)
	v_add_f32_e32 v48, v48, v49
	ds_bpermute_b32 v49, v114, v48
	global_store_dwordx4 v[70:71], v[50:53], off offset:256
	s_and_saveexec_b64 s[46:47], vcc
	s_cbranch_execz .LBB0_746
	s_waitcnt lgkmcnt(0)
	v_add_f32_e32 v50, v48, v49
	s_lshl_b32 s26, s12, 2
	v_lshlrev_b64 v[48:49], 6, v[64:65]
	s_ashr_i32 s27, s26, 31
	v_lshl_add_u64 v[48:49], s[10:11], 0, v[48:49]
	v_lshl_add_u64 v[48:49], s[26:27], 2, v[48:49]
	s_lshl_b32 s14, s60, 2
	v_lshl_add_u64 v[48:49], v[48:49], 0, s[14:15]
	global_store_dword v[48:49], v50, off
.LBB0_746:
	s_or_b64 exec, exec, s[46:47]
	v_add_u32_e32 v48, 0x90, v146
	s_waitcnt lgkmcnt(0)
	v_ashrrev_i32_e32 v49, 31, v48
	v_lshlrev_b64 v[50:51], 11, v[48:49]
	v_lshl_add_u64 v[50:51], s[18:19], 0, v[50:51]
	v_lshl_add_u64 v[54:55], v[144:145], 1, v[50:51]
	s_waitcnt vmcnt(20)
	v_mov_b32_e32 v50, v208
	v_mov_b32_e32 v51, v209
	v_mov_b32_e32 v52, v210
	v_mov_b32_e32 v53, v211
	v_lshlrev_b32_e32 v56, 16, v50
	v_and_b32_e32 v57, 0xffff0000, v50
	v_lshlrev_b32_e32 v50, 16, v51
	v_and_b32_e32 v51, 0xffff0000, v51
	v_lshlrev_b32_e32 v58, 16, v52
	v_and_b32_e32 v59, 0xffff0000, v52
	v_lshlrev_b32_e32 v52, 16, v53
	v_and_b32_e32 v53, 0xffff0000, v53
	v_pk_add_f32 v[50:51], v[46:47], v[50:51]
	v_pk_add_f32 v[56:57], v[44:45], v[56:57]
	v_pk_add_f32 v[52:53], v[42:43], v[52:53]
	v_pk_add_f32 v[58:59], v[40:41], v[58:59]
	v_cvt_pk_bf16_f32 v40, v56, v57
	v_cvt_pk_bf16_f32 v41, v50, v51
	v_mul_f32_e32 v57, v57, v57
	v_cvt_pk_bf16_f32 v42, v58, v59
	v_cvt_pk_bf16_f32 v43, v52, v53
	v_mul_f32_e32 v51, v51, v51
	v_mul_f32_e32 v59, v59, v59
	v_mul_f32_e32 v53, v53, v53
	v_fmac_f32_e32 v57, v56, v56
	v_fmac_f32_e32 v51, v50, v50
	v_fmac_f32_e32 v59, v58, v58
	v_fmac_f32_e32 v53, v52, v52
	v_add_f32_e32 v50, v57, v51
	v_add_f32_e32 v51, v59, v53
	v_add_f32_e32 v56, v50, v51
	global_store_dwordx4 v[54:55], v[40:43], off
	s_waitcnt vmcnt(20)
	v_mov_b32_e32 v44, v212
	v_mov_b32_e32 v45, v213
	v_mov_b32_e32 v46, v214
	v_mov_b32_e32 v47, v215
	v_lshlrev_b32_e32 v50, 16, v44
	v_and_b32_e32 v51, 0xffff0000, v44
	v_lshlrev_b32_e32 v44, 16, v45
	v_and_b32_e32 v45, 0xffff0000, v45
	v_lshlrev_b32_e32 v52, 16, v46
	v_and_b32_e32 v53, 0xffff0000, v46
	v_lshlrev_b32_e32 v46, 16, v47
	v_and_b32_e32 v47, 0xffff0000, v47
	v_pk_add_f32 v[38:39], v[38:39], v[44:45]
	v_pk_add_f32 v[36:37], v[36:37], v[50:51]
	v_pk_add_f32 v[44:45], v[34:35], v[46:47]
	v_pk_add_f32 v[46:47], v[32:33], v[52:53]
	v_mul_f32_e32 v32, v37, v37
	v_mul_f32_e32 v33, v39, v39
	v_mul_f32_e32 v34, v47, v47
	v_mul_f32_e32 v35, v45, v45
	v_fmac_f32_e32 v32, v36, v36
	v_fmac_f32_e32 v33, v38, v38
	v_fmac_f32_e32 v34, v46, v46
	v_fmac_f32_e32 v35, v44, v44
	v_add_f32_e32 v32, v32, v33
	v_add_f32_e32 v33, v34, v35
	v_add_f32_e32 v32, v32, v33
	v_add_f32_e32 v32, v56, v32
	ds_bpermute_b32 v33, v120, v32
	v_cvt_pk_bf16_f32 v34, v36, v37
	v_cvt_pk_bf16_f32 v35, v38, v39
	v_cvt_pk_bf16_f32 v36, v46, v47
	v_cvt_pk_bf16_f32 v37, v44, v45
	s_waitcnt lgkmcnt(0)
	v_add_f32_e32 v32, v32, v33
	ds_bpermute_b32 v33, v114, v32
	global_store_dwordx4 v[54:55], v[34:37], off offset:256
	s_and_saveexec_b64 s[46:47], vcc
	s_cbranch_execz .LBB0_748
	s_waitcnt lgkmcnt(0)
	v_add_f32_e32 v34, v32, v33
	s_lshl_b32 s26, s12, 2
	v_lshlrev_b64 v[32:33], 6, v[48:49]
	s_ashr_i32 s27, s26, 31
	v_lshl_add_u64 v[32:33], s[10:11], 0, v[32:33]
	v_lshl_add_u64 v[32:33], s[26:27], 2, v[32:33]
	s_lshl_b32 s14, s60, 2
	v_lshl_add_u64 v[32:33], v[32:33], 0, s[14:15]
	global_store_dword v[32:33], v34, off
.LBB0_748:
	s_or_b64 exec, exec, s[46:47]
	v_add_u32_e32 v32, 0xa0, v146
	s_waitcnt lgkmcnt(0)
	v_ashrrev_i32_e32 v33, 31, v32
	v_lshlrev_b64 v[34:35], 11, v[32:33]
	v_lshl_add_u64 v[34:35], s[18:19], 0, v[34:35]
	v_lshl_add_u64 v[38:39], v[144:145], 1, v[34:35]
	s_waitcnt vmcnt(21)
	v_mov_b32_e32 v34, v216
	v_mov_b32_e32 v35, v217
	v_mov_b32_e32 v36, v218
	v_mov_b32_e32 v37, v219
	v_lshlrev_b32_e32 v40, 16, v34
	v_and_b32_e32 v41, 0xffff0000, v34
	v_lshlrev_b32_e32 v34, 16, v35
	v_and_b32_e32 v35, 0xffff0000, v35
	v_lshlrev_b32_e32 v42, 16, v36
	v_and_b32_e32 v43, 0xffff0000, v36
	v_lshlrev_b32_e32 v36, 16, v37
	v_and_b32_e32 v37, 0xffff0000, v37
	v_pk_add_f32 v[34:35], v[30:31], v[34:35]
	v_pk_add_f32 v[40:41], v[28:29], v[40:41]
	v_pk_add_f32 v[36:37], v[26:27], v[36:37]
	v_pk_add_f32 v[42:43], v[24:25], v[42:43]
	v_cvt_pk_bf16_f32 v24, v40, v41
	v_cvt_pk_bf16_f32 v25, v34, v35
	v_mul_f32_e32 v41, v41, v41
	v_cvt_pk_bf16_f32 v26, v42, v43
	v_cvt_pk_bf16_f32 v27, v36, v37
	v_mul_f32_e32 v35, v35, v35
	v_mul_f32_e32 v43, v43, v43
	v_mul_f32_e32 v37, v37, v37
	v_fmac_f32_e32 v41, v40, v40
	v_fmac_f32_e32 v35, v34, v34
	v_fmac_f32_e32 v43, v42, v42
	v_fmac_f32_e32 v37, v36, v36
	v_add_f32_e32 v34, v41, v35
	v_add_f32_e32 v35, v43, v37
	v_add_f32_e32 v40, v34, v35
	global_store_dwordx4 v[38:39], v[24:27], off
	s_waitcnt vmcnt(21)
	v_mov_b32_e32 v28, v220
	v_mov_b32_e32 v29, v221
	v_mov_b32_e32 v30, v222
	v_mov_b32_e32 v31, v223
	v_lshlrev_b32_e32 v34, 16, v28
	v_and_b32_e32 v35, 0xffff0000, v28
	v_lshlrev_b32_e32 v28, 16, v29
	v_and_b32_e32 v29, 0xffff0000, v29
	v_lshlrev_b32_e32 v36, 16, v30
	v_and_b32_e32 v37, 0xffff0000, v30
	v_lshlrev_b32_e32 v30, 16, v31
	v_and_b32_e32 v31, 0xffff0000, v31
	v_pk_add_f32 v[22:23], v[22:23], v[28:29]
	v_pk_add_f32 v[20:21], v[20:21], v[34:35]
	v_pk_add_f32 v[28:29], v[18:19], v[30:31]
	v_pk_add_f32 v[30:31], v[16:17], v[36:37]
	v_mul_f32_e32 v16, v21, v21
	v_mul_f32_e32 v17, v23, v23
	v_mul_f32_e32 v18, v31, v31
	v_mul_f32_e32 v19, v29, v29
	v_fmac_f32_e32 v16, v20, v20
	v_fmac_f32_e32 v17, v22, v22
	v_fmac_f32_e32 v18, v30, v30
	v_fmac_f32_e32 v19, v28, v28
	v_add_f32_e32 v16, v16, v17
	v_add_f32_e32 v17, v18, v19
	v_add_f32_e32 v16, v16, v17
	v_add_f32_e32 v16, v40, v16
	ds_bpermute_b32 v17, v120, v16
	v_cvt_pk_bf16_f32 v18, v20, v21
	v_cvt_pk_bf16_f32 v19, v22, v23
	v_cvt_pk_bf16_f32 v20, v30, v31
	v_cvt_pk_bf16_f32 v21, v28, v29
	s_waitcnt lgkmcnt(0)
	v_add_f32_e32 v16, v16, v17
	ds_bpermute_b32 v17, v114, v16
	global_store_dwordx4 v[38:39], v[18:21], off offset:256
	s_and_saveexec_b64 s[46:47], vcc
	s_cbranch_execz .LBB0_750
	s_waitcnt lgkmcnt(0)
	v_add_f32_e32 v18, v16, v17
	s_lshl_b32 s26, s12, 2
	v_lshlrev_b64 v[16:17], 6, v[32:33]
	s_ashr_i32 s27, s26, 31
	v_lshl_add_u64 v[16:17], s[10:11], 0, v[16:17]
	v_lshl_add_u64 v[16:17], s[26:27], 2, v[16:17]
	s_lshl_b32 s14, s60, 2
	v_lshl_add_u64 v[16:17], v[16:17], 0, s[14:15]
	global_store_dword v[16:17], v18, off
.LBB0_750:
	s_or_b64 exec, exec, s[46:47]
	v_add_u32_e32 v16, 0xb0, v146
	s_waitcnt lgkmcnt(0)
	v_ashrrev_i32_e32 v17, 31, v16
	v_lshlrev_b64 v[18:19], 11, v[16:17]
	v_lshl_add_u64 v[18:19], s[18:19], 0, v[18:19]
	v_lshl_add_u64 v[22:23], v[144:145], 1, v[18:19]
	s_waitcnt vmcnt(22)
	v_mov_b32_e32 v18, v226
	v_mov_b32_e32 v19, v227
	v_mov_b32_e32 v20, v228
	v_mov_b32_e32 v21, v229
	v_lshlrev_b32_e32 v24, 16, v18
	v_and_b32_e32 v25, 0xffff0000, v18
	v_lshlrev_b32_e32 v18, 16, v19
	v_and_b32_e32 v19, 0xffff0000, v19
	v_lshlrev_b32_e32 v26, 16, v20
	v_and_b32_e32 v27, 0xffff0000, v20
	v_lshlrev_b32_e32 v20, 16, v21
	v_and_b32_e32 v21, 0xffff0000, v21
	v_pk_add_f32 v[18:19], v[14:15], v[18:19]
	v_pk_add_f32 v[24:25], v[12:13], v[24:25]
	v_pk_add_f32 v[20:21], v[10:11], v[20:21]
	v_pk_add_f32 v[26:27], v[8:9], v[26:27]
	v_cvt_pk_bf16_f32 v8, v24, v25
	v_cvt_pk_bf16_f32 v9, v18, v19
	v_mul_f32_e32 v25, v25, v25
	v_cvt_pk_bf16_f32 v10, v26, v27
	v_cvt_pk_bf16_f32 v11, v20, v21
	v_mul_f32_e32 v19, v19, v19
	v_mul_f32_e32 v27, v27, v27
	v_mul_f32_e32 v21, v21, v21
	v_fmac_f32_e32 v25, v24, v24
	v_fmac_f32_e32 v19, v18, v18
	v_fmac_f32_e32 v27, v26, v26
	v_fmac_f32_e32 v21, v20, v20
	v_add_f32_e32 v18, v25, v19
	v_add_f32_e32 v19, v27, v21
	v_add_f32_e32 v24, v18, v19
	global_store_dwordx4 v[22:23], v[8:11], off
	s_waitcnt vmcnt(22)
	v_mov_b32_e32 v12, v230
	v_mov_b32_e32 v13, v231
	v_mov_b32_e32 v14, v232
	v_mov_b32_e32 v15, v233
	v_lshlrev_b32_e32 v18, 16, v12
	v_and_b32_e32 v19, 0xffff0000, v12
	v_lshlrev_b32_e32 v12, 16, v13
	v_and_b32_e32 v13, 0xffff0000, v13
	v_lshlrev_b32_e32 v20, 16, v14
	v_and_b32_e32 v21, 0xffff0000, v14
	v_lshlrev_b32_e32 v14, 16, v15
	v_and_b32_e32 v15, 0xffff0000, v15
	v_pk_add_f32 v[6:7], v[6:7], v[12:13]
	v_pk_add_f32 v[4:5], v[4:5], v[18:19]
	v_pk_add_f32 v[12:13], v[2:3], v[14:15]
	v_pk_add_f32 v[14:15], v[0:1], v[20:21]
	v_mul_f32_e32 v0, v5, v5
	v_mul_f32_e32 v1, v7, v7
	v_mul_f32_e32 v2, v15, v15
	v_mul_f32_e32 v3, v13, v13
	v_fmac_f32_e32 v0, v4, v4
	v_fmac_f32_e32 v1, v6, v6
	v_fmac_f32_e32 v2, v14, v14
	v_fmac_f32_e32 v3, v12, v12
	v_add_f32_e32 v0, v0, v1
	v_add_f32_e32 v1, v2, v3
	v_add_f32_e32 v0, v0, v1
	v_add_f32_e32 v0, v24, v0
	ds_bpermute_b32 v1, v120, v0
	v_cvt_pk_bf16_f32 v2, v4, v5
	v_cvt_pk_bf16_f32 v3, v6, v7
	v_cvt_pk_bf16_f32 v4, v14, v15
	v_cvt_pk_bf16_f32 v5, v12, v13
	s_waitcnt lgkmcnt(0)
	v_add_f32_e32 v0, v0, v1
	ds_bpermute_b32 v1, v114, v0
	global_store_dwordx4 v[22:23], v[2:5], off offset:256
	s_and_saveexec_b64 s[46:47], vcc
	s_cbranch_execz .LBB0_752
	s_waitcnt lgkmcnt(0)
	v_add_f32_e32 v2, v0, v1
	s_lshl_b32 s26, s12, 2
	v_lshlrev_b64 v[0:1], 6, v[16:17]
	s_ashr_i32 s27, s26, 31
	v_lshl_add_u64 v[0:1], s[10:11], 0, v[0:1]
	v_lshl_add_u64 v[0:1], s[26:27], 2, v[0:1]
	s_lshl_b32 s14, s60, 2
	v_lshl_add_u64 v[0:1], v[0:1], 0, s[14:15]
	global_store_dword v[0:1], v2, off

.LBB0_1062:
	s_lshl_b32 s16, s16, 8
	v_mov_b32_e32 v166, v149
	v_mov_b32_e32 v167, v148
	s_add_i32 s16, s16, s63
	s_lshl_b32 s22, s56, 8
	v_add_u32_e32 v146, s16, v166
	s_or_b32 s22, s22, s64
	v_ashrrev_i32_e32 v147, 31, v146
	v_lshl_add_u32 v144, v167, 3, s22
	v_lshlrev_b64 v[154:155], 11, v[146:147]
	v_ashrrev_i32_e32 v145, 31, v144
	v_lshl_add_u64 v[154:155], s[36:37], 0, v[154:155]
	v_lshl_add_u64 v[158:159], v[144:145], 1, v[154:155]
	v_mov_b32_e32 v236, 0x8000
	v_mov_b32_e32 v237, 0
	v_mov_b32_e32 v238, 0x28000
	v_mov_b32_e32 v239, 0
	global_load_dwordx4 v[168:171], v[158:159], off
	global_load_dwordx4 v[172:175], v[158:159], off offset:256
	v_lshl_add_u64 v[234:235], v[158:159], 0, v[236:237]
	global_load_dwordx4 v[176:179], v[234:235], off
	global_load_dwordx4 v[180:183], v[234:235], off offset:256
	v_lshl_add_u64 v[234:235], v[234:235], 0, v[236:237]
	global_load_dwordx4 v[184:187], v[234:235], off
	global_load_dwordx4 v[188:191], v[234:235], off offset:256
	v_lshl_add_u64 v[234:235], v[234:235], 0, v[236:237]
	global_load_dwordx4 v[192:195], v[234:235], off
	global_load_dwordx4 v[196:199], v[234:235], off offset:256
	v_lshl_add_u64 v[234:235], v[234:235], 0, v[238:239]
	global_load_dwordx4 v[200:203], v[234:235], off
	global_load_dwordx4 v[204:207], v[234:235], off offset:256
	v_lshl_add_u64 v[234:235], v[234:235], 0, v[236:237]
	global_load_dwordx4 v[208:211], v[234:235], off
	global_load_dwordx4 v[212:215], v[234:235], off offset:256
	v_lshl_add_u64 v[234:235], v[234:235], 0, v[236:237]
	global_load_dwordx4 v[216:219], v[234:235], off
	global_load_dwordx4 v[220:223], v[234:235], off offset:256
	v_lshl_add_u64 v[234:235], v[234:235], 0, v[236:237]
	global_load_dwordx4 v[226:229], v[234:235], off
	global_load_dwordx4 v[230:233], v[234:235], off offset:256
	v_cmp_eq_u32_e32 vcc, 0, v167
	s_waitcnt vmcnt(15)
	v_mov_b32_e32 v154, v168
	v_mov_b32_e32 v155, v169
	v_mov_b32_e32 v156, v170
	v_mov_b32_e32 v157, v171
	v_lshlrev_b32_e32 v160, 16, v154
	v_and_b32_e32 v161, 0xffff0000, v154
	v_lshlrev_b32_e32 v154, 16, v155
	v_and_b32_e32 v155, 0xffff0000, v155
	v_lshlrev_b32_e32 v162, 16, v156
	v_and_b32_e32 v163, 0xffff0000, v156
	v_lshlrev_b32_e32 v156, 16, v157
	v_and_b32_e32 v157, 0xffff0000, v157
	v_pk_add_f32 v[126:127], v[126:127], v[154:155]
	v_pk_add_f32 v[160:161], v[124:125], v[160:161]
	v_pk_add_f32 v[164:165], v[122:123], v[156:157]
	v_pk_add_f32 v[162:163], v[120:121], v[162:163]
	v_cvt_pk_bf16_f32 v122, v160, v161
	v_cvt_pk_bf16_f32 v123, v126, v127
	v_mul_f32_e32 v161, v161, v161
	v_cvt_pk_bf16_f32 v124, v162, v163
	v_cvt_pk_bf16_f32 v125, v164, v165
	v_mul_f32_e32 v127, v127, v127
	v_mul_f32_e32 v163, v163, v163
	v_mul_f32_e32 v165, v165, v165
	v_fmac_f32_e32 v161, v160, v160
	v_fmac_f32_e32 v127, v126, v126
	v_fmac_f32_e32 v163, v162, v162
	v_fmac_f32_e32 v165, v164, v164
	v_add_f32_e32 v126, v161, v127
	v_add_f32_e32 v127, v163, v165
	v_add_f32_e32 v162, v126, v127
	v_lshlrev_b32_e32 v120, 2, v166
	v_lshl_add_u32 v121, v167, 6, v120
	v_xor_b32_e32 v120, 64, v121
	global_store_dwordx4 v[158:159], v[122:125], off
	s_waitcnt vmcnt(15)
	v_mov_b32_e32 v154, v172
	v_mov_b32_e32 v155, v173
	v_mov_b32_e32 v156, v174
	v_mov_b32_e32 v157, v175
	v_lshlrev_b32_e32 v126, 16, v154
	v_and_b32_e32 v127, 0xffff0000, v154
	v_lshlrev_b32_e32 v154, 16, v155
	v_and_b32_e32 v155, 0xffff0000, v155
	v_lshlrev_b32_e32 v160, 16, v156
	v_and_b32_e32 v161, 0xffff0000, v156
	v_lshlrev_b32_e32 v156, 16, v157
	v_and_b32_e32 v157, 0xffff0000, v157
	v_pk_add_f32 v[118:119], v[118:119], v[154:155]
	v_pk_add_f32 v[116:117], v[116:117], v[126:127]
	v_pk_add_f32 v[126:127], v[114:115], v[156:157]
	v_pk_add_f32 v[154:155], v[112:113], v[160:161]
	v_mul_f32_e32 v112, v117, v117
	v_mul_f32_e32 v113, v119, v119
	v_mul_f32_e32 v114, v155, v155
	v_mul_f32_e32 v115, v127, v127
	v_fmac_f32_e32 v112, v116, v116
	v_fmac_f32_e32 v113, v118, v118
	v_fmac_f32_e32 v114, v154, v154
	v_fmac_f32_e32 v115, v126, v126
	v_add_f32_e32 v112, v112, v113
	v_add_f32_e32 v113, v114, v115
	v_add_f32_e32 v112, v112, v113
	v_add_f32_e32 v112, v162, v112
	ds_bpermute_b32 v113, v120, v112
	v_xor_b32_e32 v114, 0x80, v121
	v_cvt_pk_bf16_f32 v116, v116, v117
	v_cvt_pk_bf16_f32 v117, v118, v119
	v_cvt_pk_bf16_f32 v118, v154, v155
	s_waitcnt lgkmcnt(0)
	v_add_f32_e32 v112, v112, v113
	ds_bpermute_b32 v113, v114, v112
	v_cvt_pk_bf16_f32 v119, v126, v127
	global_store_dwordx4 v[158:159], v[116:119], off offset:256
	s_and_saveexec_b64 s[44:45], vcc
	s_cbranch_execz .LBB0_1064
	s_waitcnt lgkmcnt(0)
	v_add_f32_e32 v115, v112, v113
	s_lshl_b32 s22, s56, 2
	v_lshlrev_b64 v[112:113], 6, v[146:147]
	s_ashr_i32 s23, s22, 31
	v_lshl_add_u64 v[112:113], s[14:15], 0, v[112:113]
	v_lshl_add_u64 v[112:113], s[22:23], 2, v[112:113]
	s_lshl_b32 s16, s62, 2
	v_lshl_add_u64 v[112:113], v[112:113], 0, s[16:17]
	global_store_dword v[112:113], v115, off
.LBB0_1064:
	s_or_b64 exec, exec, s[44:45]
	v_add_u32_e32 v112, 16, v146
	s_waitcnt lgkmcnt(0)
	v_ashrrev_i32_e32 v113, 31, v112
	v_lshlrev_b64 v[116:117], 11, v[112:113]
	v_lshl_add_u64 v[116:117], s[36:37], 0, v[116:117]
	v_lshl_add_u64 v[122:123], v[144:145], 1, v[116:117]
	s_waitcnt vmcnt(16)
	v_mov_b32_e32 v116, v176
	v_mov_b32_e32 v117, v177
	v_mov_b32_e32 v118, v178
	v_mov_b32_e32 v119, v179
	v_lshlrev_b32_e32 v124, 16, v116
	v_and_b32_e32 v125, 0xffff0000, v116
	v_lshlrev_b32_e32 v116, 16, v117
	v_and_b32_e32 v117, 0xffff0000, v117
	v_lshlrev_b32_e32 v126, 16, v118
	v_and_b32_e32 v127, 0xffff0000, v118
	v_lshlrev_b32_e32 v118, 16, v119
	v_and_b32_e32 v119, 0xffff0000, v119
	v_pk_add_f32 v[116:117], v[110:111], v[116:117]
	v_pk_add_f32 v[124:125], v[108:109], v[124:125]
	v_pk_add_f32 v[118:119], v[106:107], v[118:119]
	v_pk_add_f32 v[126:127], v[104:105], v[126:127]
	v_cvt_pk_bf16_f32 v104, v124, v125
	v_cvt_pk_bf16_f32 v105, v116, v117
	v_mul_f32_e32 v115, v125, v125
	v_cvt_pk_bf16_f32 v106, v126, v127
	v_cvt_pk_bf16_f32 v107, v118, v119
	v_mul_f32_e32 v117, v117, v117
	v_mul_f32_e32 v121, v127, v127
	v_mul_f32_e32 v119, v119, v119
	v_fmac_f32_e32 v115, v124, v124
	v_fmac_f32_e32 v117, v116, v116
	v_fmac_f32_e32 v121, v126, v126
	v_fmac_f32_e32 v119, v118, v118
	v_add_f32_e32 v115, v115, v117
	v_add_f32_e32 v116, v121, v119
	v_add_f32_e32 v115, v115, v116
	global_store_dwordx4 v[122:123], v[104:107], off
	s_waitcnt vmcnt(16)
	v_mov_b32_e32 v108, v180
	v_mov_b32_e32 v109, v181
	v_mov_b32_e32 v110, v182
	v_mov_b32_e32 v111, v183
	v_lshlrev_b32_e32 v116, 16, v108
	v_and_b32_e32 v117, 0xffff0000, v108
	v_lshlrev_b32_e32 v108, 16, v109
	v_and_b32_e32 v109, 0xffff0000, v109
	v_lshlrev_b32_e32 v118, 16, v110
	v_and_b32_e32 v119, 0xffff0000, v110
	v_lshlrev_b32_e32 v110, 16, v111
	v_and_b32_e32 v111, 0xffff0000, v111
	v_pk_add_f32 v[102:103], v[102:103], v[108:109]
	v_pk_add_f32 v[100:101], v[100:101], v[116:117]
	v_pk_add_f32 v[108:109], v[98:99], v[110:111]
	v_pk_add_f32 v[110:111], v[96:97], v[118:119]
	v_mul_f32_e32 v96, v101, v101
	v_mul_f32_e32 v97, v103, v103
	v_mul_f32_e32 v98, v111, v111
	v_mul_f32_e32 v99, v109, v109
	v_fmac_f32_e32 v96, v100, v100
	v_fmac_f32_e32 v97, v102, v102
	v_fmac_f32_e32 v98, v110, v110
	v_fmac_f32_e32 v99, v108, v108
	v_add_f32_e32 v96, v96, v97
	v_add_f32_e32 v97, v98, v99
	v_add_f32_e32 v96, v96, v97
	v_add_f32_e32 v96, v115, v96
	ds_bpermute_b32 v97, v120, v96
	v_cvt_pk_bf16_f32 v98, v100, v101
	v_cvt_pk_bf16_f32 v99, v102, v103
	v_cvt_pk_bf16_f32 v100, v110, v111
	v_cvt_pk_bf16_f32 v101, v108, v109
	s_waitcnt lgkmcnt(0)
	v_add_f32_e32 v96, v96, v97
	ds_bpermute_b32 v97, v114, v96
	global_store_dwordx4 v[122:123], v[98:101], off offset:256
	s_and_saveexec_b64 s[44:45], vcc
	s_cbranch_execz .LBB0_1066
	s_waitcnt lgkmcnt(0)
	v_add_f32_e32 v98, v96, v97
	s_lshl_b32 s22, s56, 2
	v_lshlrev_b64 v[96:97], 6, v[112:113]
	s_ashr_i32 s23, s22, 31
	v_lshl_add_u64 v[96:97], s[14:15], 0, v[96:97]
	v_lshl_add_u64 v[96:97], s[22:23], 2, v[96:97]
	s_lshl_b32 s16, s62, 2
	v_lshl_add_u64 v[96:97], v[96:97], 0, s[16:17]
	global_store_dword v[96:97], v98, off
.LBB0_1066:
	s_or_b64 exec, exec, s[44:45]
	v_add_u32_e32 v96, 32, v146
	s_waitcnt lgkmcnt(0)
	v_ashrrev_i32_e32 v97, 31, v96
	v_lshlrev_b64 v[98:99], 11, v[96:97]
	v_lshl_add_u64 v[98:99], s[36:37], 0, v[98:99]
	v_lshl_add_u64 v[102:103], v[144:145], 1, v[98:99]
	s_waitcnt vmcnt(17)
	v_mov_b32_e32 v98, v184
	v_mov_b32_e32 v99, v185
	v_mov_b32_e32 v100, v186
	v_mov_b32_e32 v101, v187
	v_lshlrev_b32_e32 v104, 16, v98
	v_and_b32_e32 v105, 0xffff0000, v98
	v_lshlrev_b32_e32 v98, 16, v99
	v_and_b32_e32 v99, 0xffff0000, v99
	v_lshlrev_b32_e32 v106, 16, v100
	v_and_b32_e32 v107, 0xffff0000, v100
	v_lshlrev_b32_e32 v100, 16, v101
	v_and_b32_e32 v101, 0xffff0000, v101
	v_pk_add_f32 v[98:99], v[94:95], v[98:99]
	v_pk_add_f32 v[104:105], v[92:93], v[104:105]
	v_pk_add_f32 v[100:101], v[90:91], v[100:101]
	v_pk_add_f32 v[106:107], v[88:89], v[106:107]
	v_cvt_pk_bf16_f32 v88, v104, v105
	v_cvt_pk_bf16_f32 v89, v98, v99
	v_mul_f32_e32 v105, v105, v105
	v_cvt_pk_bf16_f32 v90, v106, v107
	v_cvt_pk_bf16_f32 v91, v100, v101
	v_mul_f32_e32 v99, v99, v99
	v_mul_f32_e32 v107, v107, v107
	v_mul_f32_e32 v101, v101, v101
	v_fmac_f32_e32 v105, v104, v104
	v_fmac_f32_e32 v99, v98, v98
	v_fmac_f32_e32 v107, v106, v106
	v_fmac_f32_e32 v101, v100, v100
	v_add_f32_e32 v98, v105, v99
	v_add_f32_e32 v99, v107, v101
	v_add_f32_e32 v104, v98, v99
	global_store_dwordx4 v[102:103], v[88:91], off
	s_waitcnt vmcnt(17)
	v_mov_b32_e32 v92, v188
	v_mov_b32_e32 v93, v189
	v_mov_b32_e32 v94, v190
	v_mov_b32_e32 v95, v191
	v_lshlrev_b32_e32 v98, 16, v92
	v_and_b32_e32 v99, 0xffff0000, v92
	v_lshlrev_b32_e32 v92, 16, v93
	v_and_b32_e32 v93, 0xffff0000, v93
	v_lshlrev_b32_e32 v100, 16, v94
	v_and_b32_e32 v101, 0xffff0000, v94
	v_lshlrev_b32_e32 v94, 16, v95
	v_and_b32_e32 v95, 0xffff0000, v95
	v_pk_add_f32 v[86:87], v[86:87], v[92:93]
	v_pk_add_f32 v[84:85], v[84:85], v[98:99]
	v_pk_add_f32 v[92:93], v[82:83], v[94:95]
	v_pk_add_f32 v[94:95], v[80:81], v[100:101]
	v_mul_f32_e32 v80, v85, v85
	v_mul_f32_e32 v81, v87, v87
	v_mul_f32_e32 v82, v95, v95
	v_mul_f32_e32 v83, v93, v93
	v_fmac_f32_e32 v80, v84, v84
	v_fmac_f32_e32 v81, v86, v86
	v_fmac_f32_e32 v82, v94, v94
	v_fmac_f32_e32 v83, v92, v92
	v_add_f32_e32 v80, v80, v81
	v_add_f32_e32 v81, v82, v83
	v_add_f32_e32 v80, v80, v81
	v_add_f32_e32 v80, v104, v80
	ds_bpermute_b32 v81, v120, v80
	v_cvt_pk_bf16_f32 v82, v84, v85
	v_cvt_pk_bf16_f32 v83, v86, v87
	v_cvt_pk_bf16_f32 v84, v94, v95
	v_cvt_pk_bf16_f32 v85, v92, v93
	s_waitcnt lgkmcnt(0)
	v_add_f32_e32 v80, v80, v81
	ds_bpermute_b32 v81, v114, v80
	global_store_dwordx4 v[102:103], v[82:85], off offset:256
	s_and_saveexec_b64 s[44:45], vcc
	s_cbranch_execz .LBB0_1068
	s_waitcnt lgkmcnt(0)
	v_add_f32_e32 v82, v80, v81
	s_lshl_b32 s22, s56, 2
	v_lshlrev_b64 v[80:81], 6, v[96:97]
	s_ashr_i32 s23, s22, 31
	v_lshl_add_u64 v[80:81], s[14:15], 0, v[80:81]
	v_lshl_add_u64 v[80:81], s[22:23], 2, v[80:81]
	s_lshl_b32 s16, s62, 2
	v_lshl_add_u64 v[80:81], v[80:81], 0, s[16:17]
	global_store_dword v[80:81], v82, off
.LBB0_1068:
	s_or_b64 exec, exec, s[44:45]
	v_add_u32_e32 v80, 48, v146
	s_waitcnt lgkmcnt(0)
	v_ashrrev_i32_e32 v81, 31, v80
	v_lshlrev_b64 v[82:83], 11, v[80:81]
	v_lshl_add_u64 v[82:83], s[36:37], 0, v[82:83]
	v_lshl_add_u64 v[86:87], v[144:145], 1, v[82:83]
	s_waitcnt vmcnt(18)
	v_mov_b32_e32 v82, v192
	v_mov_b32_e32 v83, v193
	v_mov_b32_e32 v84, v194
	v_mov_b32_e32 v85, v195
	v_lshlrev_b32_e32 v88, 16, v82
	v_and_b32_e32 v89, 0xffff0000, v82
	v_lshlrev_b32_e32 v82, 16, v83
	v_and_b32_e32 v83, 0xffff0000, v83
	v_lshlrev_b32_e32 v90, 16, v84
	v_and_b32_e32 v91, 0xffff0000, v84
	v_lshlrev_b32_e32 v84, 16, v85
	v_and_b32_e32 v85, 0xffff0000, v85
	v_pk_add_f32 v[82:83], v[78:79], v[82:83]
	v_pk_add_f32 v[88:89], v[76:77], v[88:89]
	v_pk_add_f32 v[84:85], v[74:75], v[84:85]
	v_pk_add_f32 v[90:91], v[72:73], v[90:91]
	v_cvt_pk_bf16_f32 v72, v88, v89
	v_cvt_pk_bf16_f32 v73, v82, v83
	v_mul_f32_e32 v89, v89, v89
	v_cvt_pk_bf16_f32 v74, v90, v91
	v_cvt_pk_bf16_f32 v75, v84, v85
	v_mul_f32_e32 v83, v83, v83
	v_mul_f32_e32 v91, v91, v91
	v_mul_f32_e32 v85, v85, v85
	v_fmac_f32_e32 v89, v88, v88
	v_fmac_f32_e32 v83, v82, v82
	v_fmac_f32_e32 v91, v90, v90
	v_fmac_f32_e32 v85, v84, v84
	v_add_f32_e32 v82, v89, v83
	v_add_f32_e32 v83, v91, v85
	v_add_f32_e32 v88, v82, v83
	global_store_dwordx4 v[86:87], v[72:75], off
	s_waitcnt vmcnt(18)
	v_mov_b32_e32 v76, v196
	v_mov_b32_e32 v77, v197
	v_mov_b32_e32 v78, v198
	v_mov_b32_e32 v79, v199
	v_lshlrev_b32_e32 v82, 16, v76
	v_and_b32_e32 v83, 0xffff0000, v76
	v_lshlrev_b32_e32 v76, 16, v77
	v_and_b32_e32 v77, 0xffff0000, v77
	v_lshlrev_b32_e32 v84, 16, v78
	v_and_b32_e32 v85, 0xffff0000, v78
	v_lshlrev_b32_e32 v78, 16, v79
	v_and_b32_e32 v79, 0xffff0000, v79
	v_pk_add_f32 v[70:71], v[70:71], v[76:77]
	v_pk_add_f32 v[68:69], v[68:69], v[82:83]
	v_pk_add_f32 v[76:77], v[66:67], v[78:79]
	v_pk_add_f32 v[78:79], v[64:65], v[84:85]
	v_mul_f32_e32 v64, v69, v69
	v_mul_f32_e32 v65, v71, v71
	v_mul_f32_e32 v66, v79, v79
	v_mul_f32_e32 v67, v77, v77
	v_fmac_f32_e32 v64, v68, v68
	v_fmac_f32_e32 v65, v70, v70
	v_fmac_f32_e32 v66, v78, v78
	v_fmac_f32_e32 v67, v76, v76
	v_add_f32_e32 v64, v64, v65
	v_add_f32_e32 v65, v66, v67
	v_add_f32_e32 v64, v64, v65
	v_add_f32_e32 v64, v88, v64
	ds_bpermute_b32 v65, v120, v64
	v_cvt_pk_bf16_f32 v66, v68, v69
	v_cvt_pk_bf16_f32 v67, v70, v71
	v_cvt_pk_bf16_f32 v68, v78, v79
	v_cvt_pk_bf16_f32 v69, v76, v77
	s_waitcnt lgkmcnt(0)
	v_add_f32_e32 v64, v64, v65
	ds_bpermute_b32 v65, v114, v64
	global_store_dwordx4 v[86:87], v[66:69], off offset:256
	s_and_saveexec_b64 s[44:45], vcc
	s_cbranch_execz .LBB0_1070
	s_waitcnt lgkmcnt(0)
	v_add_f32_e32 v66, v64, v65
	s_lshl_b32 s22, s56, 2
	v_lshlrev_b64 v[64:65], 6, v[80:81]
	s_ashr_i32 s23, s22, 31
	v_lshl_add_u64 v[64:65], s[14:15], 0, v[64:65]
	v_lshl_add_u64 v[64:65], s[22:23], 2, v[64:65]
	s_lshl_b32 s16, s62, 2
	v_lshl_add_u64 v[64:65], v[64:65], 0, s[16:17]
	global_store_dword v[64:65], v66, off
.LBB0_1070:
	s_or_b64 exec, exec, s[44:45]
	v_add_u32_e32 v64, 0x80, v146
	s_waitcnt lgkmcnt(0)
	v_ashrrev_i32_e32 v65, 31, v64
	v_lshlrev_b64 v[66:67], 11, v[64:65]
	v_lshl_add_u64 v[66:67], s[36:37], 0, v[66:67]
	v_lshl_add_u64 v[70:71], v[144:145], 1, v[66:67]
	s_waitcnt vmcnt(19)
	v_mov_b32_e32 v66, v200
	v_mov_b32_e32 v67, v201
	v_mov_b32_e32 v68, v202
	v_mov_b32_e32 v69, v203
	v_lshlrev_b32_e32 v72, 16, v66
	v_and_b32_e32 v73, 0xffff0000, v66
	v_lshlrev_b32_e32 v66, 16, v67
	v_and_b32_e32 v67, 0xffff0000, v67
	v_lshlrev_b32_e32 v74, 16, v68
	v_and_b32_e32 v75, 0xffff0000, v68
	v_lshlrev_b32_e32 v68, 16, v69
	v_and_b32_e32 v69, 0xffff0000, v69
	v_pk_add_f32 v[66:67], v[62:63], v[66:67]
	v_pk_add_f32 v[72:73], v[60:61], v[72:73]
	v_pk_add_f32 v[68:69], v[58:59], v[68:69]
	v_pk_add_f32 v[74:75], v[56:57], v[74:75]
	v_cvt_pk_bf16_f32 v56, v72, v73
	v_cvt_pk_bf16_f32 v57, v66, v67
	v_mul_f32_e32 v73, v73, v73
	v_cvt_pk_bf16_f32 v58, v74, v75
	v_cvt_pk_bf16_f32 v59, v68, v69
	v_mul_f32_e32 v67, v67, v67
	v_mul_f32_e32 v75, v75, v75
	v_mul_f32_e32 v69, v69, v69
	v_fmac_f32_e32 v73, v72, v72
	v_fmac_f32_e32 v67, v66, v66
	v_fmac_f32_e32 v75, v74, v74
	v_fmac_f32_e32 v69, v68, v68
	v_add_f32_e32 v66, v73, v67
	v_add_f32_e32 v67, v75, v69
	v_add_f32_e32 v72, v66, v67
	global_store_dwordx4 v[70:71], v[56:59], off
	s_waitcnt vmcnt(19)
	v_mov_b32_e32 v60, v204
	v_mov_b32_e32 v61, v205
	v_mov_b32_e32 v62, v206
	v_mov_b32_e32 v63, v207
	v_lshlrev_b32_e32 v66, 16, v60
	v_and_b32_e32 v67, 0xffff0000, v60
	v_lshlrev_b32_e32 v60, 16, v61
	v_and_b32_e32 v61, 0xffff0000, v61
	v_lshlrev_b32_e32 v68, 16, v62
	v_and_b32_e32 v69, 0xffff0000, v62
	v_lshlrev_b32_e32 v62, 16, v63
	v_and_b32_e32 v63, 0xffff0000, v63
	v_pk_add_f32 v[54:55], v[54:55], v[60:61]
	v_pk_add_f32 v[52:53], v[52:53], v[66:67]
	v_pk_add_f32 v[60:61], v[50:51], v[62:63]
	v_pk_add_f32 v[62:63], v[48:49], v[68:69]
	v_mul_f32_e32 v48, v53, v53
	v_mul_f32_e32 v49, v55, v55
	v_mul_f32_e32 v50, v63, v63
	v_mul_f32_e32 v51, v61, v61
	v_fmac_f32_e32 v48, v52, v52
	v_fmac_f32_e32 v49, v54, v54
	v_fmac_f32_e32 v50, v62, v62
	v_fmac_f32_e32 v51, v60, v60
	v_add_f32_e32 v48, v48, v49
	v_add_f32_e32 v49, v50, v51
	v_add_f32_e32 v48, v48, v49
	v_add_f32_e32 v48, v72, v48
	ds_bpermute_b32 v49, v120, v48
	v_cvt_pk_bf16_f32 v50, v52, v53
	v_cvt_pk_bf16_f32 v51, v54, v55
	v_cvt_pk_bf16_f32 v52, v62, v63
	v_cvt_pk_bf16_f32 v53, v60, v61
	s_waitcnt lgkmcnt(0)
	v_add_f32_e32 v48, v48, v49
	ds_bpermute_b32 v49, v114, v48
	global_store_dwordx4 v[70:71], v[50:53], off offset:256
	s_and_saveexec_b64 s[44:45], vcc
	s_cbranch_execz .LBB0_1072
	s_waitcnt lgkmcnt(0)
	v_add_f32_e32 v50, v48, v49
	s_lshl_b32 s22, s56, 2
	v_lshlrev_b64 v[48:49], 6, v[64:65]
	s_ashr_i32 s23, s22, 31
	v_lshl_add_u64 v[48:49], s[14:15], 0, v[48:49]
	v_lshl_add_u64 v[48:49], s[22:23], 2, v[48:49]
	s_lshl_b32 s16, s62, 2
	v_lshl_add_u64 v[48:49], v[48:49], 0, s[16:17]
	global_store_dword v[48:49], v50, off
.LBB0_1072:
	s_or_b64 exec, exec, s[44:45]
	v_add_u32_e32 v48, 0x90, v146
	s_waitcnt lgkmcnt(0)
	v_ashrrev_i32_e32 v49, 31, v48
	v_lshlrev_b64 v[50:51], 11, v[48:49]
	v_lshl_add_u64 v[50:51], s[36:37], 0, v[50:51]
	v_lshl_add_u64 v[54:55], v[144:145], 1, v[50:51]
	s_waitcnt vmcnt(20)
	v_mov_b32_e32 v50, v208
	v_mov_b32_e32 v51, v209
	v_mov_b32_e32 v52, v210
	v_mov_b32_e32 v53, v211
	v_lshlrev_b32_e32 v56, 16, v50
	v_and_b32_e32 v57, 0xffff0000, v50
	v_lshlrev_b32_e32 v50, 16, v51
	v_and_b32_e32 v51, 0xffff0000, v51
	v_lshlrev_b32_e32 v58, 16, v52
	v_and_b32_e32 v59, 0xffff0000, v52
	v_lshlrev_b32_e32 v52, 16, v53
	v_and_b32_e32 v53, 0xffff0000, v53
	v_pk_add_f32 v[50:51], v[46:47], v[50:51]
	v_pk_add_f32 v[56:57], v[44:45], v[56:57]
	v_pk_add_f32 v[52:53], v[42:43], v[52:53]
	v_pk_add_f32 v[58:59], v[40:41], v[58:59]
	v_cvt_pk_bf16_f32 v40, v56, v57
	v_cvt_pk_bf16_f32 v41, v50, v51
	v_mul_f32_e32 v57, v57, v57
	v_cvt_pk_bf16_f32 v42, v58, v59
	v_cvt_pk_bf16_f32 v43, v52, v53
	v_mul_f32_e32 v51, v51, v51
	v_mul_f32_e32 v59, v59, v59
	v_mul_f32_e32 v53, v53, v53
	v_fmac_f32_e32 v57, v56, v56
	v_fmac_f32_e32 v51, v50, v50
	v_fmac_f32_e32 v59, v58, v58
	v_fmac_f32_e32 v53, v52, v52
	v_add_f32_e32 v50, v57, v51
	v_add_f32_e32 v51, v59, v53
	v_add_f32_e32 v56, v50, v51
	global_store_dwordx4 v[54:55], v[40:43], off
	s_waitcnt vmcnt(20)
	v_mov_b32_e32 v44, v212
	v_mov_b32_e32 v45, v213
	v_mov_b32_e32 v46, v214
	v_mov_b32_e32 v47, v215
	v_lshlrev_b32_e32 v50, 16, v44
	v_and_b32_e32 v51, 0xffff0000, v44
	v_lshlrev_b32_e32 v44, 16, v45
	v_and_b32_e32 v45, 0xffff0000, v45
	v_lshlrev_b32_e32 v52, 16, v46
	v_and_b32_e32 v53, 0xffff0000, v46
	v_lshlrev_b32_e32 v46, 16, v47
	v_and_b32_e32 v47, 0xffff0000, v47
	v_pk_add_f32 v[38:39], v[38:39], v[44:45]
	v_pk_add_f32 v[36:37], v[36:37], v[50:51]
	v_pk_add_f32 v[44:45], v[34:35], v[46:47]
	v_pk_add_f32 v[46:47], v[32:33], v[52:53]
	v_mul_f32_e32 v32, v37, v37
	v_mul_f32_e32 v33, v39, v39
	v_mul_f32_e32 v34, v47, v47
	v_mul_f32_e32 v35, v45, v45
	v_fmac_f32_e32 v32, v36, v36
	v_fmac_f32_e32 v33, v38, v38
	v_fmac_f32_e32 v34, v46, v46
	v_fmac_f32_e32 v35, v44, v44
	v_add_f32_e32 v32, v32, v33
	v_add_f32_e32 v33, v34, v35
	v_add_f32_e32 v32, v32, v33
	v_add_f32_e32 v32, v56, v32
	ds_bpermute_b32 v33, v120, v32
	v_cvt_pk_bf16_f32 v34, v36, v37
	v_cvt_pk_bf16_f32 v35, v38, v39
	v_cvt_pk_bf16_f32 v36, v46, v47
	v_cvt_pk_bf16_f32 v37, v44, v45
	s_waitcnt lgkmcnt(0)
	v_add_f32_e32 v32, v32, v33
	ds_bpermute_b32 v33, v114, v32
	global_store_dwordx4 v[54:55], v[34:37], off offset:256
	s_and_saveexec_b64 s[44:45], vcc
	s_cbranch_execz .LBB0_1074
	s_waitcnt lgkmcnt(0)
	v_add_f32_e32 v34, v32, v33
	s_lshl_b32 s22, s56, 2
	v_lshlrev_b64 v[32:33], 6, v[48:49]
	s_ashr_i32 s23, s22, 31
	v_lshl_add_u64 v[32:33], s[14:15], 0, v[32:33]
	v_lshl_add_u64 v[32:33], s[22:23], 2, v[32:33]
	s_lshl_b32 s16, s62, 2
	v_lshl_add_u64 v[32:33], v[32:33], 0, s[16:17]
	global_store_dword v[32:33], v34, off
.LBB0_1074:
	s_or_b64 exec, exec, s[44:45]
	v_add_u32_e32 v32, 0xa0, v146
	s_waitcnt lgkmcnt(0)
	v_ashrrev_i32_e32 v33, 31, v32
	v_lshlrev_b64 v[34:35], 11, v[32:33]
	v_lshl_add_u64 v[34:35], s[36:37], 0, v[34:35]
	v_lshl_add_u64 v[38:39], v[144:145], 1, v[34:35]
	s_waitcnt vmcnt(21)
	v_mov_b32_e32 v34, v216
	v_mov_b32_e32 v35, v217
	v_mov_b32_e32 v36, v218
	v_mov_b32_e32 v37, v219
	v_lshlrev_b32_e32 v40, 16, v34
	v_and_b32_e32 v41, 0xffff0000, v34
	v_lshlrev_b32_e32 v34, 16, v35
	v_and_b32_e32 v35, 0xffff0000, v35
	v_lshlrev_b32_e32 v42, 16, v36
	v_and_b32_e32 v43, 0xffff0000, v36
	v_lshlrev_b32_e32 v36, 16, v37
	v_and_b32_e32 v37, 0xffff0000, v37
	v_pk_add_f32 v[34:35], v[30:31], v[34:35]
	v_pk_add_f32 v[40:41], v[28:29], v[40:41]
	v_pk_add_f32 v[36:37], v[26:27], v[36:37]
	v_pk_add_f32 v[42:43], v[24:25], v[42:43]
	v_cvt_pk_bf16_f32 v24, v40, v41
	v_cvt_pk_bf16_f32 v25, v34, v35
	v_mul_f32_e32 v41, v41, v41
	v_cvt_pk_bf16_f32 v26, v42, v43
	v_cvt_pk_bf16_f32 v27, v36, v37
	v_mul_f32_e32 v35, v35, v35
	v_mul_f32_e32 v43, v43, v43
	v_mul_f32_e32 v37, v37, v37
	v_fmac_f32_e32 v41, v40, v40
	v_fmac_f32_e32 v35, v34, v34
	v_fmac_f32_e32 v43, v42, v42
	v_fmac_f32_e32 v37, v36, v36
	v_add_f32_e32 v34, v41, v35
	v_add_f32_e32 v35, v43, v37
	v_add_f32_e32 v40, v34, v35
	global_store_dwordx4 v[38:39], v[24:27], off
	s_waitcnt vmcnt(21)
	v_mov_b32_e32 v28, v220
	v_mov_b32_e32 v29, v221
	v_mov_b32_e32 v30, v222
	v_mov_b32_e32 v31, v223
	v_lshlrev_b32_e32 v34, 16, v28
	v_and_b32_e32 v35, 0xffff0000, v28
	v_lshlrev_b32_e32 v28, 16, v29
	v_and_b32_e32 v29, 0xffff0000, v29
	v_lshlrev_b32_e32 v36, 16, v30
	v_and_b32_e32 v37, 0xffff0000, v30
	v_lshlrev_b32_e32 v30, 16, v31
	v_and_b32_e32 v31, 0xffff0000, v31
	v_pk_add_f32 v[22:23], v[22:23], v[28:29]
	v_pk_add_f32 v[20:21], v[20:21], v[34:35]
	v_pk_add_f32 v[28:29], v[18:19], v[30:31]
	v_pk_add_f32 v[30:31], v[16:17], v[36:37]
	v_mul_f32_e32 v16, v21, v21
	v_mul_f32_e32 v17, v23, v23
	v_mul_f32_e32 v18, v31, v31
	v_mul_f32_e32 v19, v29, v29
	v_fmac_f32_e32 v16, v20, v20
	v_fmac_f32_e32 v17, v22, v22
	v_fmac_f32_e32 v18, v30, v30
	v_fmac_f32_e32 v19, v28, v28
	v_add_f32_e32 v16, v16, v17
	v_add_f32_e32 v17, v18, v19
	v_add_f32_e32 v16, v16, v17
	v_add_f32_e32 v16, v40, v16
	ds_bpermute_b32 v17, v120, v16
	v_cvt_pk_bf16_f32 v18, v20, v21
	v_cvt_pk_bf16_f32 v19, v22, v23
	v_cvt_pk_bf16_f32 v20, v30, v31
	v_cvt_pk_bf16_f32 v21, v28, v29
	s_waitcnt lgkmcnt(0)
	v_add_f32_e32 v16, v16, v17
	ds_bpermute_b32 v17, v114, v16
	global_store_dwordx4 v[38:39], v[18:21], off offset:256
	s_and_saveexec_b64 s[44:45], vcc
	s_cbranch_execz .LBB0_1076
	s_waitcnt lgkmcnt(0)
	v_add_f32_e32 v18, v16, v17
	s_lshl_b32 s22, s56, 2
	v_lshlrev_b64 v[16:17], 6, v[32:33]
	s_ashr_i32 s23, s22, 31
	v_lshl_add_u64 v[16:17], s[14:15], 0, v[16:17]
	v_lshl_add_u64 v[16:17], s[22:23], 2, v[16:17]
	s_lshl_b32 s16, s62, 2
	v_lshl_add_u64 v[16:17], v[16:17], 0, s[16:17]
	global_store_dword v[16:17], v18, off
.LBB0_1076:
	s_or_b64 exec, exec, s[44:45]
	v_add_u32_e32 v16, 0xb0, v146
	s_waitcnt lgkmcnt(0)
	v_ashrrev_i32_e32 v17, 31, v16
	v_lshlrev_b64 v[18:19], 11, v[16:17]
	v_lshl_add_u64 v[18:19], s[36:37], 0, v[18:19]
	v_lshl_add_u64 v[22:23], v[144:145], 1, v[18:19]
	s_waitcnt vmcnt(22)
	v_mov_b32_e32 v18, v226
	v_mov_b32_e32 v19, v227
	v_mov_b32_e32 v20, v228
	v_mov_b32_e32 v21, v229
	v_lshlrev_b32_e32 v24, 16, v18
	v_and_b32_e32 v25, 0xffff0000, v18
	v_lshlrev_b32_e32 v18, 16, v19
	v_and_b32_e32 v19, 0xffff0000, v19
	v_lshlrev_b32_e32 v26, 16, v20
	v_and_b32_e32 v27, 0xffff0000, v20
	v_lshlrev_b32_e32 v20, 16, v21
	v_and_b32_e32 v21, 0xffff0000, v21
	v_pk_add_f32 v[18:19], v[14:15], v[18:19]
	v_pk_add_f32 v[24:25], v[12:13], v[24:25]
	v_pk_add_f32 v[20:21], v[10:11], v[20:21]
	v_pk_add_f32 v[26:27], v[8:9], v[26:27]
	v_cvt_pk_bf16_f32 v8, v24, v25
	v_cvt_pk_bf16_f32 v9, v18, v19
	v_mul_f32_e32 v25, v25, v25
	v_cvt_pk_bf16_f32 v10, v26, v27
	v_cvt_pk_bf16_f32 v11, v20, v21
	v_mul_f32_e32 v19, v19, v19
	v_mul_f32_e32 v27, v27, v27
	v_mul_f32_e32 v21, v21, v21
	v_fmac_f32_e32 v25, v24, v24
	v_fmac_f32_e32 v19, v18, v18
	v_fmac_f32_e32 v27, v26, v26
	v_fmac_f32_e32 v21, v20, v20
	v_add_f32_e32 v18, v25, v19
	v_add_f32_e32 v19, v27, v21
	v_add_f32_e32 v24, v18, v19
	global_store_dwordx4 v[22:23], v[8:11], off
	s_waitcnt vmcnt(22)
	v_mov_b32_e32 v12, v230
	v_mov_b32_e32 v13, v231
	v_mov_b32_e32 v14, v232
	v_mov_b32_e32 v15, v233
	v_lshlrev_b32_e32 v18, 16, v12
	v_and_b32_e32 v19, 0xffff0000, v12
	v_lshlrev_b32_e32 v12, 16, v13
	v_and_b32_e32 v13, 0xffff0000, v13
	v_lshlrev_b32_e32 v20, 16, v14
	v_and_b32_e32 v21, 0xffff0000, v14
	v_lshlrev_b32_e32 v14, 16, v15
	v_and_b32_e32 v15, 0xffff0000, v15
	v_pk_add_f32 v[6:7], v[6:7], v[12:13]
	v_pk_add_f32 v[4:5], v[4:5], v[18:19]
	v_pk_add_f32 v[12:13], v[2:3], v[14:15]
	v_pk_add_f32 v[14:15], v[0:1], v[20:21]
	v_mul_f32_e32 v0, v5, v5
	v_mul_f32_e32 v1, v7, v7
	v_mul_f32_e32 v2, v15, v15
	v_mul_f32_e32 v3, v13, v13
	v_fmac_f32_e32 v0, v4, v4
	v_fmac_f32_e32 v1, v6, v6
	v_fmac_f32_e32 v2, v14, v14
	v_fmac_f32_e32 v3, v12, v12
	v_add_f32_e32 v0, v0, v1
	v_add_f32_e32 v1, v2, v3
	v_add_f32_e32 v0, v0, v1
	v_add_f32_e32 v0, v24, v0
	ds_bpermute_b32 v1, v120, v0
	v_cvt_pk_bf16_f32 v2, v4, v5
	v_cvt_pk_bf16_f32 v3, v6, v7
	v_cvt_pk_bf16_f32 v4, v14, v15
	v_cvt_pk_bf16_f32 v5, v12, v13
	s_waitcnt lgkmcnt(0)
	v_add_f32_e32 v0, v0, v1
	ds_bpermute_b32 v1, v114, v0
	global_store_dwordx4 v[22:23], v[2:5], off offset:256
	s_and_saveexec_b64 s[44:45], vcc
	s_cbranch_execz .LBB0_1078
	s_waitcnt lgkmcnt(0)
	v_add_f32_e32 v2, v0, v1
	s_lshl_b32 s22, s56, 2
	v_lshlrev_b64 v[0:1], 6, v[16:17]
	s_ashr_i32 s23, s22, 31
	v_lshl_add_u64 v[0:1], s[14:15], 0, v[0:1]
	v_lshl_add_u64 v[0:1], s[22:23], 2, v[0:1]
	s_lshl_b32 s16, s62, 2
	v_lshl_add_u64 v[0:1], v[0:1], 0, s[16:17]
	global_store_dword v[0:1], v2, off

.LBB0_1606:
	s_lshl_b32 s16, s16, 8
	v_mov_b32_e32 v166, v149
	v_mov_b32_e32 v167, v148
	s_add_i32 s16, s16, s61
	s_lshl_b32 s26, s14, 8
	v_add_u32_e32 v146, s16, v166
	s_or_b32 s26, s26, s62
	v_ashrrev_i32_e32 v147, 31, v146
	v_lshl_add_u32 v144, v167, 3, s26
	v_lshlrev_b64 v[154:155], 11, v[146:147]
	v_ashrrev_i32_e32 v145, 31, v144
	v_lshl_add_u64 v[154:155], s[20:21], 0, v[154:155]
	v_lshl_add_u64 v[158:159], v[144:145], 1, v[154:155]
	v_mov_b32_e32 v236, 0x8000
	v_mov_b32_e32 v237, 0
	v_mov_b32_e32 v238, 0x28000
	v_mov_b32_e32 v239, 0
	global_load_dwordx4 v[168:171], v[158:159], off
	global_load_dwordx4 v[172:175], v[158:159], off offset:256
	v_lshl_add_u64 v[234:235], v[158:159], 0, v[236:237]
	global_load_dwordx4 v[176:179], v[234:235], off
	global_load_dwordx4 v[180:183], v[234:235], off offset:256
	v_lshl_add_u64 v[234:235], v[234:235], 0, v[236:237]
	global_load_dwordx4 v[184:187], v[234:235], off
	global_load_dwordx4 v[188:191], v[234:235], off offset:256
	v_lshl_add_u64 v[234:235], v[234:235], 0, v[236:237]
	global_load_dwordx4 v[192:195], v[234:235], off
	global_load_dwordx4 v[196:199], v[234:235], off offset:256
	v_lshl_add_u64 v[234:235], v[234:235], 0, v[238:239]
	global_load_dwordx4 v[200:203], v[234:235], off
	global_load_dwordx4 v[204:207], v[234:235], off offset:256
	v_lshl_add_u64 v[234:235], v[234:235], 0, v[236:237]
	global_load_dwordx4 v[208:211], v[234:235], off
	global_load_dwordx4 v[212:215], v[234:235], off offset:256
	v_lshl_add_u64 v[234:235], v[234:235], 0, v[236:237]
	global_load_dwordx4 v[216:219], v[234:235], off
	global_load_dwordx4 v[220:223], v[234:235], off offset:256
	v_lshl_add_u64 v[234:235], v[234:235], 0, v[236:237]
	global_load_dwordx4 v[226:229], v[234:235], off
	global_load_dwordx4 v[230:233], v[234:235], off offset:256
	v_cmp_eq_u32_e32 vcc, 0, v167
	s_waitcnt vmcnt(15)
	v_mov_b32_e32 v154, v168
	v_mov_b32_e32 v155, v169
	v_mov_b32_e32 v156, v170
	v_mov_b32_e32 v157, v171
	v_lshlrev_b32_e32 v160, 16, v154
	v_and_b32_e32 v161, 0xffff0000, v154
	v_lshlrev_b32_e32 v154, 16, v155
	v_and_b32_e32 v155, 0xffff0000, v155
	v_lshlrev_b32_e32 v162, 16, v156
	v_and_b32_e32 v163, 0xffff0000, v156
	v_lshlrev_b32_e32 v156, 16, v157
	v_and_b32_e32 v157, 0xffff0000, v157
	v_pk_add_f32 v[126:127], v[126:127], v[154:155]
	v_pk_add_f32 v[160:161], v[124:125], v[160:161]
	v_pk_add_f32 v[164:165], v[122:123], v[156:157]
	v_pk_add_f32 v[162:163], v[120:121], v[162:163]
	v_cvt_pk_bf16_f32 v122, v160, v161
	v_cvt_pk_bf16_f32 v123, v126, v127
	v_mul_f32_e32 v161, v161, v161
	v_cvt_pk_bf16_f32 v124, v162, v163
	v_cvt_pk_bf16_f32 v125, v164, v165
	v_mul_f32_e32 v127, v127, v127
	v_mul_f32_e32 v163, v163, v163
	v_mul_f32_e32 v165, v165, v165
	v_fmac_f32_e32 v161, v160, v160
	v_fmac_f32_e32 v127, v126, v126
	v_fmac_f32_e32 v163, v162, v162
	v_fmac_f32_e32 v165, v164, v164
	v_add_f32_e32 v126, v161, v127
	v_add_f32_e32 v127, v163, v165
	v_add_f32_e32 v162, v126, v127
	v_lshlrev_b32_e32 v120, 2, v166
	v_lshl_add_u32 v121, v167, 6, v120
	v_xor_b32_e32 v120, 64, v121
	global_store_dwordx4 v[158:159], v[122:125], off
	s_waitcnt vmcnt(15)
	v_mov_b32_e32 v154, v172
	v_mov_b32_e32 v155, v173
	v_mov_b32_e32 v156, v174
	v_mov_b32_e32 v157, v175
	v_lshlrev_b32_e32 v126, 16, v154
	v_and_b32_e32 v127, 0xffff0000, v154
	v_lshlrev_b32_e32 v154, 16, v155
	v_and_b32_e32 v155, 0xffff0000, v155
	v_lshlrev_b32_e32 v160, 16, v156
	v_and_b32_e32 v161, 0xffff0000, v156
	v_lshlrev_b32_e32 v156, 16, v157
	v_and_b32_e32 v157, 0xffff0000, v157
	v_pk_add_f32 v[118:119], v[118:119], v[154:155]
	v_pk_add_f32 v[116:117], v[116:117], v[126:127]
	v_pk_add_f32 v[126:127], v[114:115], v[156:157]
	v_pk_add_f32 v[154:155], v[112:113], v[160:161]
	v_mul_f32_e32 v112, v117, v117
	v_mul_f32_e32 v113, v119, v119
	v_mul_f32_e32 v114, v155, v155
	v_mul_f32_e32 v115, v127, v127
	v_fmac_f32_e32 v112, v116, v116
	v_fmac_f32_e32 v113, v118, v118
	v_fmac_f32_e32 v114, v154, v154
	v_fmac_f32_e32 v115, v126, v126
	v_add_f32_e32 v112, v112, v113
	v_add_f32_e32 v113, v114, v115
	v_add_f32_e32 v112, v112, v113
	v_add_f32_e32 v112, v162, v112
	ds_bpermute_b32 v113, v120, v112
	v_xor_b32_e32 v114, 0x80, v121
	v_cvt_pk_bf16_f32 v116, v116, v117
	v_cvt_pk_bf16_f32 v117, v118, v119
	v_cvt_pk_bf16_f32 v118, v154, v155
	s_waitcnt lgkmcnt(0)
	v_add_f32_e32 v112, v112, v113
	ds_bpermute_b32 v113, v114, v112
	v_cvt_pk_bf16_f32 v119, v126, v127
	global_store_dwordx4 v[158:159], v[116:119], off offset:256
	s_and_saveexec_b64 s[46:47], vcc
	s_cbranch_execz .LBB0_1608
	s_waitcnt lgkmcnt(0)
	v_add_f32_e32 v115, v112, v113
	s_lshl_b32 s26, s14, 2
	v_lshlrev_b64 v[112:113], 6, v[146:147]
	s_ashr_i32 s27, s26, 31
	v_lshl_add_u64 v[112:113], s[12:13], 0, v[112:113]
	v_lshl_add_u64 v[112:113], s[26:27], 2, v[112:113]
	s_lshl_b32 s16, s60, 2
	v_lshl_add_u64 v[112:113], v[112:113], 0, s[16:17]
	global_store_dword v[112:113], v115, off
.LBB0_1608:
	s_or_b64 exec, exec, s[46:47]
	v_add_u32_e32 v112, 16, v146
	s_waitcnt lgkmcnt(0)
	v_ashrrev_i32_e32 v113, 31, v112
	v_lshlrev_b64 v[116:117], 11, v[112:113]
	v_lshl_add_u64 v[116:117], s[20:21], 0, v[116:117]
	v_lshl_add_u64 v[122:123], v[144:145], 1, v[116:117]
	s_waitcnt vmcnt(16)
	v_mov_b32_e32 v116, v176
	v_mov_b32_e32 v117, v177
	v_mov_b32_e32 v118, v178
	v_mov_b32_e32 v119, v179
	v_lshlrev_b32_e32 v124, 16, v116
	v_and_b32_e32 v125, 0xffff0000, v116
	v_lshlrev_b32_e32 v116, 16, v117
	v_and_b32_e32 v117, 0xffff0000, v117
	v_lshlrev_b32_e32 v126, 16, v118
	v_and_b32_e32 v127, 0xffff0000, v118
	v_lshlrev_b32_e32 v118, 16, v119
	v_and_b32_e32 v119, 0xffff0000, v119
	v_pk_add_f32 v[116:117], v[110:111], v[116:117]
	v_pk_add_f32 v[124:125], v[108:109], v[124:125]
	v_pk_add_f32 v[118:119], v[106:107], v[118:119]
	v_pk_add_f32 v[126:127], v[104:105], v[126:127]
	v_cvt_pk_bf16_f32 v104, v124, v125
	v_cvt_pk_bf16_f32 v105, v116, v117
	v_mul_f32_e32 v115, v125, v125
	v_cvt_pk_bf16_f32 v106, v126, v127
	v_cvt_pk_bf16_f32 v107, v118, v119
	v_mul_f32_e32 v117, v117, v117
	v_mul_f32_e32 v121, v127, v127
	v_mul_f32_e32 v119, v119, v119
	v_fmac_f32_e32 v115, v124, v124
	v_fmac_f32_e32 v117, v116, v116
	v_fmac_f32_e32 v121, v126, v126
	v_fmac_f32_e32 v119, v118, v118
	v_add_f32_e32 v115, v115, v117
	v_add_f32_e32 v116, v121, v119
	v_add_f32_e32 v115, v115, v116
	global_store_dwordx4 v[122:123], v[104:107], off
	s_waitcnt vmcnt(16)
	v_mov_b32_e32 v108, v180
	v_mov_b32_e32 v109, v181
	v_mov_b32_e32 v110, v182
	v_mov_b32_e32 v111, v183
	v_lshlrev_b32_e32 v116, 16, v108
	v_and_b32_e32 v117, 0xffff0000, v108
	v_lshlrev_b32_e32 v108, 16, v109
	v_and_b32_e32 v109, 0xffff0000, v109
	v_lshlrev_b32_e32 v118, 16, v110
	v_and_b32_e32 v119, 0xffff0000, v110
	v_lshlrev_b32_e32 v110, 16, v111
	v_and_b32_e32 v111, 0xffff0000, v111
	v_pk_add_f32 v[102:103], v[102:103], v[108:109]
	v_pk_add_f32 v[100:101], v[100:101], v[116:117]
	v_pk_add_f32 v[108:109], v[98:99], v[110:111]
	v_pk_add_f32 v[110:111], v[96:97], v[118:119]
	v_mul_f32_e32 v96, v101, v101
	v_mul_f32_e32 v97, v103, v103
	v_mul_f32_e32 v98, v111, v111
	v_mul_f32_e32 v99, v109, v109
	v_fmac_f32_e32 v96, v100, v100
	v_fmac_f32_e32 v97, v102, v102
	v_fmac_f32_e32 v98, v110, v110
	v_fmac_f32_e32 v99, v108, v108
	v_add_f32_e32 v96, v96, v97
	v_add_f32_e32 v97, v98, v99
	v_add_f32_e32 v96, v96, v97
	v_add_f32_e32 v96, v115, v96
	ds_bpermute_b32 v97, v120, v96
	v_cvt_pk_bf16_f32 v98, v100, v101
	v_cvt_pk_bf16_f32 v99, v102, v103
	v_cvt_pk_bf16_f32 v100, v110, v111
	v_cvt_pk_bf16_f32 v101, v108, v109
	s_waitcnt lgkmcnt(0)
	v_add_f32_e32 v96, v96, v97
	ds_bpermute_b32 v97, v114, v96
	global_store_dwordx4 v[122:123], v[98:101], off offset:256
	s_and_saveexec_b64 s[46:47], vcc
	s_cbranch_execz .LBB0_1610
	s_waitcnt lgkmcnt(0)
	v_add_f32_e32 v98, v96, v97
	s_lshl_b32 s26, s14, 2
	v_lshlrev_b64 v[96:97], 6, v[112:113]
	s_ashr_i32 s27, s26, 31
	v_lshl_add_u64 v[96:97], s[12:13], 0, v[96:97]
	v_lshl_add_u64 v[96:97], s[26:27], 2, v[96:97]
	s_lshl_b32 s16, s60, 2
	v_lshl_add_u64 v[96:97], v[96:97], 0, s[16:17]
	global_store_dword v[96:97], v98, off
.LBB0_1610:
	s_or_b64 exec, exec, s[46:47]
	v_add_u32_e32 v96, 32, v146
	s_waitcnt lgkmcnt(0)
	v_ashrrev_i32_e32 v97, 31, v96
	v_lshlrev_b64 v[98:99], 11, v[96:97]
	v_lshl_add_u64 v[98:99], s[20:21], 0, v[98:99]
	v_lshl_add_u64 v[102:103], v[144:145], 1, v[98:99]
	s_waitcnt vmcnt(17)
	v_mov_b32_e32 v98, v184
	v_mov_b32_e32 v99, v185
	v_mov_b32_e32 v100, v186
	v_mov_b32_e32 v101, v187
	v_lshlrev_b32_e32 v104, 16, v98
	v_and_b32_e32 v105, 0xffff0000, v98
	v_lshlrev_b32_e32 v98, 16, v99
	v_and_b32_e32 v99, 0xffff0000, v99
	v_lshlrev_b32_e32 v106, 16, v100
	v_and_b32_e32 v107, 0xffff0000, v100
	v_lshlrev_b32_e32 v100, 16, v101
	v_and_b32_e32 v101, 0xffff0000, v101
	v_pk_add_f32 v[98:99], v[94:95], v[98:99]
	v_pk_add_f32 v[104:105], v[92:93], v[104:105]
	v_pk_add_f32 v[100:101], v[90:91], v[100:101]
	v_pk_add_f32 v[106:107], v[88:89], v[106:107]
	v_cvt_pk_bf16_f32 v88, v104, v105
	v_cvt_pk_bf16_f32 v89, v98, v99
	v_mul_f32_e32 v105, v105, v105
	v_cvt_pk_bf16_f32 v90, v106, v107
	v_cvt_pk_bf16_f32 v91, v100, v101
	v_mul_f32_e32 v99, v99, v99
	v_mul_f32_e32 v107, v107, v107
	v_mul_f32_e32 v101, v101, v101
	v_fmac_f32_e32 v105, v104, v104
	v_fmac_f32_e32 v99, v98, v98
	v_fmac_f32_e32 v107, v106, v106
	v_fmac_f32_e32 v101, v100, v100
	v_add_f32_e32 v98, v105, v99
	v_add_f32_e32 v99, v107, v101
	v_add_f32_e32 v104, v98, v99
	global_store_dwordx4 v[102:103], v[88:91], off
	s_waitcnt vmcnt(17)
	v_mov_b32_e32 v92, v188
	v_mov_b32_e32 v93, v189
	v_mov_b32_e32 v94, v190
	v_mov_b32_e32 v95, v191
	v_lshlrev_b32_e32 v98, 16, v92
	v_and_b32_e32 v99, 0xffff0000, v92
	v_lshlrev_b32_e32 v92, 16, v93
	v_and_b32_e32 v93, 0xffff0000, v93
	v_lshlrev_b32_e32 v100, 16, v94
	v_and_b32_e32 v101, 0xffff0000, v94
	v_lshlrev_b32_e32 v94, 16, v95
	v_and_b32_e32 v95, 0xffff0000, v95
	v_pk_add_f32 v[86:87], v[86:87], v[92:93]
	v_pk_add_f32 v[84:85], v[84:85], v[98:99]
	v_pk_add_f32 v[92:93], v[82:83], v[94:95]
	v_pk_add_f32 v[94:95], v[80:81], v[100:101]
	v_mul_f32_e32 v80, v85, v85
	v_mul_f32_e32 v81, v87, v87
	v_mul_f32_e32 v82, v95, v95
	v_mul_f32_e32 v83, v93, v93
	v_fmac_f32_e32 v80, v84, v84
	v_fmac_f32_e32 v81, v86, v86
	v_fmac_f32_e32 v82, v94, v94
	v_fmac_f32_e32 v83, v92, v92
	v_add_f32_e32 v80, v80, v81
	v_add_f32_e32 v81, v82, v83
	v_add_f32_e32 v80, v80, v81
	v_add_f32_e32 v80, v104, v80
	ds_bpermute_b32 v81, v120, v80
	v_cvt_pk_bf16_f32 v82, v84, v85
	v_cvt_pk_bf16_f32 v83, v86, v87
	v_cvt_pk_bf16_f32 v84, v94, v95
	v_cvt_pk_bf16_f32 v85, v92, v93
	s_waitcnt lgkmcnt(0)
	v_add_f32_e32 v80, v80, v81
	ds_bpermute_b32 v81, v114, v80
	global_store_dwordx4 v[102:103], v[82:85], off offset:256
	s_and_saveexec_b64 s[46:47], vcc
	s_cbranch_execz .LBB0_1612
	s_waitcnt lgkmcnt(0)
	v_add_f32_e32 v82, v80, v81
	s_lshl_b32 s26, s14, 2
	v_lshlrev_b64 v[80:81], 6, v[96:97]
	s_ashr_i32 s27, s26, 31
	v_lshl_add_u64 v[80:81], s[12:13], 0, v[80:81]
	v_lshl_add_u64 v[80:81], s[26:27], 2, v[80:81]
	s_lshl_b32 s16, s60, 2
	v_lshl_add_u64 v[80:81], v[80:81], 0, s[16:17]
	global_store_dword v[80:81], v82, off
.LBB0_1612:
	s_or_b64 exec, exec, s[46:47]
	v_add_u32_e32 v80, 48, v146
	s_waitcnt lgkmcnt(0)
	v_ashrrev_i32_e32 v81, 31, v80
	v_lshlrev_b64 v[82:83], 11, v[80:81]
	v_lshl_add_u64 v[82:83], s[20:21], 0, v[82:83]
	v_lshl_add_u64 v[86:87], v[144:145], 1, v[82:83]
	s_waitcnt vmcnt(18)
	v_mov_b32_e32 v82, v192
	v_mov_b32_e32 v83, v193
	v_mov_b32_e32 v84, v194
	v_mov_b32_e32 v85, v195
	v_lshlrev_b32_e32 v88, 16, v82
	v_and_b32_e32 v89, 0xffff0000, v82
	v_lshlrev_b32_e32 v82, 16, v83
	v_and_b32_e32 v83, 0xffff0000, v83
	v_lshlrev_b32_e32 v90, 16, v84
	v_and_b32_e32 v91, 0xffff0000, v84
	v_lshlrev_b32_e32 v84, 16, v85
	v_and_b32_e32 v85, 0xffff0000, v85
	v_pk_add_f32 v[82:83], v[78:79], v[82:83]
	v_pk_add_f32 v[88:89], v[76:77], v[88:89]
	v_pk_add_f32 v[84:85], v[74:75], v[84:85]
	v_pk_add_f32 v[90:91], v[72:73], v[90:91]
	v_cvt_pk_bf16_f32 v72, v88, v89
	v_cvt_pk_bf16_f32 v73, v82, v83
	v_mul_f32_e32 v89, v89, v89
	v_cvt_pk_bf16_f32 v74, v90, v91
	v_cvt_pk_bf16_f32 v75, v84, v85
	v_mul_f32_e32 v83, v83, v83
	v_mul_f32_e32 v91, v91, v91
	v_mul_f32_e32 v85, v85, v85
	v_fmac_f32_e32 v89, v88, v88
	v_fmac_f32_e32 v83, v82, v82
	v_fmac_f32_e32 v91, v90, v90
	v_fmac_f32_e32 v85, v84, v84
	v_add_f32_e32 v82, v89, v83
	v_add_f32_e32 v83, v91, v85
	v_add_f32_e32 v88, v82, v83
	global_store_dwordx4 v[86:87], v[72:75], off
	s_waitcnt vmcnt(18)
	v_mov_b32_e32 v76, v196
	v_mov_b32_e32 v77, v197
	v_mov_b32_e32 v78, v198
	v_mov_b32_e32 v79, v199
	v_lshlrev_b32_e32 v82, 16, v76
	v_and_b32_e32 v83, 0xffff0000, v76
	v_lshlrev_b32_e32 v76, 16, v77
	v_and_b32_e32 v77, 0xffff0000, v77
	v_lshlrev_b32_e32 v84, 16, v78
	v_and_b32_e32 v85, 0xffff0000, v78
	v_lshlrev_b32_e32 v78, 16, v79
	v_and_b32_e32 v79, 0xffff0000, v79
	v_pk_add_f32 v[70:71], v[70:71], v[76:77]
	v_pk_add_f32 v[68:69], v[68:69], v[82:83]
	v_pk_add_f32 v[76:77], v[66:67], v[78:79]
	v_pk_add_f32 v[78:79], v[64:65], v[84:85]
	v_mul_f32_e32 v64, v69, v69
	v_mul_f32_e32 v65, v71, v71
	v_mul_f32_e32 v66, v79, v79
	v_mul_f32_e32 v67, v77, v77
	v_fmac_f32_e32 v64, v68, v68
	v_fmac_f32_e32 v65, v70, v70
	v_fmac_f32_e32 v66, v78, v78
	v_fmac_f32_e32 v67, v76, v76
	v_add_f32_e32 v64, v64, v65
	v_add_f32_e32 v65, v66, v67
	v_add_f32_e32 v64, v64, v65
	v_add_f32_e32 v64, v88, v64
	ds_bpermute_b32 v65, v120, v64
	v_cvt_pk_bf16_f32 v66, v68, v69
	v_cvt_pk_bf16_f32 v67, v70, v71
	v_cvt_pk_bf16_f32 v68, v78, v79
	v_cvt_pk_bf16_f32 v69, v76, v77
	s_waitcnt lgkmcnt(0)
	v_add_f32_e32 v64, v64, v65
	ds_bpermute_b32 v65, v114, v64
	global_store_dwordx4 v[86:87], v[66:69], off offset:256
	s_and_saveexec_b64 s[46:47], vcc
	s_cbranch_execz .LBB0_1614
	s_waitcnt lgkmcnt(0)
	v_add_f32_e32 v66, v64, v65
	s_lshl_b32 s26, s14, 2
	v_lshlrev_b64 v[64:65], 6, v[80:81]
	s_ashr_i32 s27, s26, 31
	v_lshl_add_u64 v[64:65], s[12:13], 0, v[64:65]
	v_lshl_add_u64 v[64:65], s[26:27], 2, v[64:65]
	s_lshl_b32 s16, s60, 2
	v_lshl_add_u64 v[64:65], v[64:65], 0, s[16:17]
	global_store_dword v[64:65], v66, off
.LBB0_1614:
	s_or_b64 exec, exec, s[46:47]
	v_add_u32_e32 v64, 0x80, v146
	s_waitcnt lgkmcnt(0)
	v_ashrrev_i32_e32 v65, 31, v64
	v_lshlrev_b64 v[66:67], 11, v[64:65]
	v_lshl_add_u64 v[66:67], s[20:21], 0, v[66:67]
	v_lshl_add_u64 v[70:71], v[144:145], 1, v[66:67]
	s_waitcnt vmcnt(19)
	v_mov_b32_e32 v66, v200
	v_mov_b32_e32 v67, v201
	v_mov_b32_e32 v68, v202
	v_mov_b32_e32 v69, v203
	v_lshlrev_b32_e32 v72, 16, v66
	v_and_b32_e32 v73, 0xffff0000, v66
	v_lshlrev_b32_e32 v66, 16, v67
	v_and_b32_e32 v67, 0xffff0000, v67
	v_lshlrev_b32_e32 v74, 16, v68
	v_and_b32_e32 v75, 0xffff0000, v68
	v_lshlrev_b32_e32 v68, 16, v69
	v_and_b32_e32 v69, 0xffff0000, v69
	v_pk_add_f32 v[66:67], v[62:63], v[66:67]
	v_pk_add_f32 v[72:73], v[60:61], v[72:73]
	v_pk_add_f32 v[68:69], v[58:59], v[68:69]
	v_pk_add_f32 v[74:75], v[56:57], v[74:75]
	v_cvt_pk_bf16_f32 v56, v72, v73
	v_cvt_pk_bf16_f32 v57, v66, v67
	v_mul_f32_e32 v73, v73, v73
	v_cvt_pk_bf16_f32 v58, v74, v75
	v_cvt_pk_bf16_f32 v59, v68, v69
	v_mul_f32_e32 v67, v67, v67
	v_mul_f32_e32 v75, v75, v75
	v_mul_f32_e32 v69, v69, v69
	v_fmac_f32_e32 v73, v72, v72
	v_fmac_f32_e32 v67, v66, v66
	v_fmac_f32_e32 v75, v74, v74
	v_fmac_f32_e32 v69, v68, v68
	v_add_f32_e32 v66, v73, v67
	v_add_f32_e32 v67, v75, v69
	v_add_f32_e32 v72, v66, v67
	global_store_dwordx4 v[70:71], v[56:59], off
	s_waitcnt vmcnt(19)
	v_mov_b32_e32 v60, v204
	v_mov_b32_e32 v61, v205
	v_mov_b32_e32 v62, v206
	v_mov_b32_e32 v63, v207
	v_lshlrev_b32_e32 v66, 16, v60
	v_and_b32_e32 v67, 0xffff0000, v60
	v_lshlrev_b32_e32 v60, 16, v61
	v_and_b32_e32 v61, 0xffff0000, v61
	v_lshlrev_b32_e32 v68, 16, v62
	v_and_b32_e32 v69, 0xffff0000, v62
	v_lshlrev_b32_e32 v62, 16, v63
	v_and_b32_e32 v63, 0xffff0000, v63
	v_pk_add_f32 v[54:55], v[54:55], v[60:61]
	v_pk_add_f32 v[52:53], v[52:53], v[66:67]
	v_pk_add_f32 v[60:61], v[50:51], v[62:63]
	v_pk_add_f32 v[62:63], v[48:49], v[68:69]
	v_mul_f32_e32 v48, v53, v53
	v_mul_f32_e32 v49, v55, v55
	v_mul_f32_e32 v50, v63, v63
	v_mul_f32_e32 v51, v61, v61
	v_fmac_f32_e32 v48, v52, v52
	v_fmac_f32_e32 v49, v54, v54
	v_fmac_f32_e32 v50, v62, v62
	v_fmac_f32_e32 v51, v60, v60
	v_add_f32_e32 v48, v48, v49
	v_add_f32_e32 v49, v50, v51
	v_add_f32_e32 v48, v48, v49
	v_add_f32_e32 v48, v72, v48
	ds_bpermute_b32 v49, v120, v48
	v_cvt_pk_bf16_f32 v50, v52, v53
	v_cvt_pk_bf16_f32 v51, v54, v55
	v_cvt_pk_bf16_f32 v52, v62, v63
	v_cvt_pk_bf16_f32 v53, v60, v61
	s_waitcnt lgkmcnt(0)
	v_add_f32_e32 v48, v48, v49
	ds_bpermute_b32 v49, v114, v48
	global_store_dwordx4 v[70:71], v[50:53], off offset:256
	s_and_saveexec_b64 s[46:47], vcc
	s_cbranch_execz .LBB0_1616
	s_waitcnt lgkmcnt(0)
	v_add_f32_e32 v50, v48, v49
	s_lshl_b32 s26, s14, 2
	v_lshlrev_b64 v[48:49], 6, v[64:65]
	s_ashr_i32 s27, s26, 31
	v_lshl_add_u64 v[48:49], s[12:13], 0, v[48:49]
	v_lshl_add_u64 v[48:49], s[26:27], 2, v[48:49]
	s_lshl_b32 s16, s60, 2
	v_lshl_add_u64 v[48:49], v[48:49], 0, s[16:17]
	global_store_dword v[48:49], v50, off
.LBB0_1616:
	s_or_b64 exec, exec, s[46:47]
	v_add_u32_e32 v48, 0x90, v146
	s_waitcnt lgkmcnt(0)
	v_ashrrev_i32_e32 v49, 31, v48
	v_lshlrev_b64 v[50:51], 11, v[48:49]
	v_lshl_add_u64 v[50:51], s[20:21], 0, v[50:51]
	v_lshl_add_u64 v[54:55], v[144:145], 1, v[50:51]
	s_waitcnt vmcnt(20)
	v_mov_b32_e32 v50, v208
	v_mov_b32_e32 v51, v209
	v_mov_b32_e32 v52, v210
	v_mov_b32_e32 v53, v211
	v_lshlrev_b32_e32 v56, 16, v50
	v_and_b32_e32 v57, 0xffff0000, v50
	v_lshlrev_b32_e32 v50, 16, v51
	v_and_b32_e32 v51, 0xffff0000, v51
	v_lshlrev_b32_e32 v58, 16, v52
	v_and_b32_e32 v59, 0xffff0000, v52
	v_lshlrev_b32_e32 v52, 16, v53
	v_and_b32_e32 v53, 0xffff0000, v53
	v_pk_add_f32 v[50:51], v[46:47], v[50:51]
	v_pk_add_f32 v[56:57], v[44:45], v[56:57]
	v_pk_add_f32 v[52:53], v[42:43], v[52:53]
	v_pk_add_f32 v[58:59], v[40:41], v[58:59]
	v_cvt_pk_bf16_f32 v40, v56, v57
	v_cvt_pk_bf16_f32 v41, v50, v51
	v_mul_f32_e32 v57, v57, v57
	v_cvt_pk_bf16_f32 v42, v58, v59
	v_cvt_pk_bf16_f32 v43, v52, v53
	v_mul_f32_e32 v51, v51, v51
	v_mul_f32_e32 v59, v59, v59
	v_mul_f32_e32 v53, v53, v53
	v_fmac_f32_e32 v57, v56, v56
	v_fmac_f32_e32 v51, v50, v50
	v_fmac_f32_e32 v59, v58, v58
	v_fmac_f32_e32 v53, v52, v52
	v_add_f32_e32 v50, v57, v51
	v_add_f32_e32 v51, v59, v53
	v_add_f32_e32 v56, v50, v51
	global_store_dwordx4 v[54:55], v[40:43], off
	s_waitcnt vmcnt(20)
	v_mov_b32_e32 v44, v212
	v_mov_b32_e32 v45, v213
	v_mov_b32_e32 v46, v214
	v_mov_b32_e32 v47, v215
	v_lshlrev_b32_e32 v50, 16, v44
	v_and_b32_e32 v51, 0xffff0000, v44
	v_lshlrev_b32_e32 v44, 16, v45
	v_and_b32_e32 v45, 0xffff0000, v45
	v_lshlrev_b32_e32 v52, 16, v46
	v_and_b32_e32 v53, 0xffff0000, v46
	v_lshlrev_b32_e32 v46, 16, v47
	v_and_b32_e32 v47, 0xffff0000, v47
	v_pk_add_f32 v[38:39], v[38:39], v[44:45]
	v_pk_add_f32 v[36:37], v[36:37], v[50:51]
	v_pk_add_f32 v[44:45], v[34:35], v[46:47]
	v_pk_add_f32 v[46:47], v[32:33], v[52:53]
	v_mul_f32_e32 v32, v37, v37
	v_mul_f32_e32 v33, v39, v39
	v_mul_f32_e32 v34, v47, v47
	v_mul_f32_e32 v35, v45, v45
	v_fmac_f32_e32 v32, v36, v36
	v_fmac_f32_e32 v33, v38, v38
	v_fmac_f32_e32 v34, v46, v46
	v_fmac_f32_e32 v35, v44, v44
	v_add_f32_e32 v32, v32, v33
	v_add_f32_e32 v33, v34, v35
	v_add_f32_e32 v32, v32, v33
	v_add_f32_e32 v32, v56, v32
	ds_bpermute_b32 v33, v120, v32
	v_cvt_pk_bf16_f32 v34, v36, v37
	v_cvt_pk_bf16_f32 v35, v38, v39
	v_cvt_pk_bf16_f32 v36, v46, v47
	v_cvt_pk_bf16_f32 v37, v44, v45
	s_waitcnt lgkmcnt(0)
	v_add_f32_e32 v32, v32, v33
	ds_bpermute_b32 v33, v114, v32
	global_store_dwordx4 v[54:55], v[34:37], off offset:256
	s_and_saveexec_b64 s[46:47], vcc
	s_cbranch_execz .LBB0_1618
	s_waitcnt lgkmcnt(0)
	v_add_f32_e32 v34, v32, v33
	s_lshl_b32 s26, s14, 2
	v_lshlrev_b64 v[32:33], 6, v[48:49]
	s_ashr_i32 s27, s26, 31
	v_lshl_add_u64 v[32:33], s[12:13], 0, v[32:33]
	v_lshl_add_u64 v[32:33], s[26:27], 2, v[32:33]
	s_lshl_b32 s16, s60, 2
	v_lshl_add_u64 v[32:33], v[32:33], 0, s[16:17]
	global_store_dword v[32:33], v34, off
.LBB0_1618:
	s_or_b64 exec, exec, s[46:47]
	v_add_u32_e32 v32, 0xa0, v146
	s_waitcnt lgkmcnt(0)
	v_ashrrev_i32_e32 v33, 31, v32
	v_lshlrev_b64 v[34:35], 11, v[32:33]
	v_lshl_add_u64 v[34:35], s[20:21], 0, v[34:35]
	v_lshl_add_u64 v[38:39], v[144:145], 1, v[34:35]
	s_waitcnt vmcnt(21)
	v_mov_b32_e32 v34, v216
	v_mov_b32_e32 v35, v217
	v_mov_b32_e32 v36, v218
	v_mov_b32_e32 v37, v219
	v_lshlrev_b32_e32 v40, 16, v34
	v_and_b32_e32 v41, 0xffff0000, v34
	v_lshlrev_b32_e32 v34, 16, v35
	v_and_b32_e32 v35, 0xffff0000, v35
	v_lshlrev_b32_e32 v42, 16, v36
	v_and_b32_e32 v43, 0xffff0000, v36
	v_lshlrev_b32_e32 v36, 16, v37
	v_and_b32_e32 v37, 0xffff0000, v37
	v_pk_add_f32 v[34:35], v[30:31], v[34:35]
	v_pk_add_f32 v[40:41], v[28:29], v[40:41]
	v_pk_add_f32 v[36:37], v[26:27], v[36:37]
	v_pk_add_f32 v[42:43], v[24:25], v[42:43]
	v_cvt_pk_bf16_f32 v24, v40, v41
	v_cvt_pk_bf16_f32 v25, v34, v35
	v_mul_f32_e32 v41, v41, v41
	v_cvt_pk_bf16_f32 v26, v42, v43
	v_cvt_pk_bf16_f32 v27, v36, v37
	v_mul_f32_e32 v35, v35, v35
	v_mul_f32_e32 v43, v43, v43
	v_mul_f32_e32 v37, v37, v37
	v_fmac_f32_e32 v41, v40, v40
	v_fmac_f32_e32 v35, v34, v34
	v_fmac_f32_e32 v43, v42, v42
	v_fmac_f32_e32 v37, v36, v36
	v_add_f32_e32 v34, v41, v35
	v_add_f32_e32 v35, v43, v37
	v_add_f32_e32 v40, v34, v35
	global_store_dwordx4 v[38:39], v[24:27], off
	s_waitcnt vmcnt(21)
	v_mov_b32_e32 v28, v220
	v_mov_b32_e32 v29, v221
	v_mov_b32_e32 v30, v222
	v_mov_b32_e32 v31, v223
	v_lshlrev_b32_e32 v34, 16, v28
	v_and_b32_e32 v35, 0xffff0000, v28
	v_lshlrev_b32_e32 v28, 16, v29
	v_and_b32_e32 v29, 0xffff0000, v29
	v_lshlrev_b32_e32 v36, 16, v30
	v_and_b32_e32 v37, 0xffff0000, v30
	v_lshlrev_b32_e32 v30, 16, v31
	v_and_b32_e32 v31, 0xffff0000, v31
	v_pk_add_f32 v[22:23], v[22:23], v[28:29]
	v_pk_add_f32 v[20:21], v[20:21], v[34:35]
	v_pk_add_f32 v[28:29], v[18:19], v[30:31]
	v_pk_add_f32 v[30:31], v[16:17], v[36:37]
	v_mul_f32_e32 v16, v21, v21
	v_mul_f32_e32 v17, v23, v23
	v_mul_f32_e32 v18, v31, v31
	v_mul_f32_e32 v19, v29, v29
	v_fmac_f32_e32 v16, v20, v20
	v_fmac_f32_e32 v17, v22, v22
	v_fmac_f32_e32 v18, v30, v30
	v_fmac_f32_e32 v19, v28, v28
	v_add_f32_e32 v16, v16, v17
	v_add_f32_e32 v17, v18, v19
	v_add_f32_e32 v16, v16, v17
	v_add_f32_e32 v16, v40, v16
	ds_bpermute_b32 v17, v120, v16
	v_cvt_pk_bf16_f32 v18, v20, v21
	v_cvt_pk_bf16_f32 v19, v22, v23
	v_cvt_pk_bf16_f32 v20, v30, v31
	v_cvt_pk_bf16_f32 v21, v28, v29
	s_waitcnt lgkmcnt(0)
	v_add_f32_e32 v16, v16, v17
	ds_bpermute_b32 v17, v114, v16
	global_store_dwordx4 v[38:39], v[18:21], off offset:256
	s_and_saveexec_b64 s[46:47], vcc
	s_cbranch_execz .LBB0_1620
	s_waitcnt lgkmcnt(0)
	v_add_f32_e32 v18, v16, v17
	s_lshl_b32 s26, s14, 2
	v_lshlrev_b64 v[16:17], 6, v[32:33]
	s_ashr_i32 s27, s26, 31
	v_lshl_add_u64 v[16:17], s[12:13], 0, v[16:17]
	v_lshl_add_u64 v[16:17], s[26:27], 2, v[16:17]
	s_lshl_b32 s16, s60, 2
	v_lshl_add_u64 v[16:17], v[16:17], 0, s[16:17]
	global_store_dword v[16:17], v18, off
.LBB0_1620:
	s_or_b64 exec, exec, s[46:47]
	v_add_u32_e32 v16, 0xb0, v146
	s_waitcnt lgkmcnt(0)
	v_ashrrev_i32_e32 v17, 31, v16
	v_lshlrev_b64 v[18:19], 11, v[16:17]
	v_lshl_add_u64 v[18:19], s[20:21], 0, v[18:19]
	v_lshl_add_u64 v[22:23], v[144:145], 1, v[18:19]
	s_waitcnt vmcnt(22)
	v_mov_b32_e32 v18, v226
	v_mov_b32_e32 v19, v227
	v_mov_b32_e32 v20, v228
	v_mov_b32_e32 v21, v229
	v_lshlrev_b32_e32 v24, 16, v18
	v_and_b32_e32 v25, 0xffff0000, v18
	v_lshlrev_b32_e32 v18, 16, v19
	v_and_b32_e32 v19, 0xffff0000, v19
	v_lshlrev_b32_e32 v26, 16, v20
	v_and_b32_e32 v27, 0xffff0000, v20
	v_lshlrev_b32_e32 v20, 16, v21
	v_and_b32_e32 v21, 0xffff0000, v21
	v_pk_add_f32 v[18:19], v[14:15], v[18:19]
	v_pk_add_f32 v[24:25], v[12:13], v[24:25]
	v_pk_add_f32 v[20:21], v[10:11], v[20:21]
	v_pk_add_f32 v[26:27], v[8:9], v[26:27]
	v_cvt_pk_bf16_f32 v8, v24, v25
	v_cvt_pk_bf16_f32 v9, v18, v19
	v_mul_f32_e32 v25, v25, v25
	v_cvt_pk_bf16_f32 v10, v26, v27
	v_cvt_pk_bf16_f32 v11, v20, v21
	v_mul_f32_e32 v19, v19, v19
	v_mul_f32_e32 v27, v27, v27
	v_mul_f32_e32 v21, v21, v21
	v_fmac_f32_e32 v25, v24, v24
	v_fmac_f32_e32 v19, v18, v18
	v_fmac_f32_e32 v27, v26, v26
	v_fmac_f32_e32 v21, v20, v20
	v_add_f32_e32 v18, v25, v19
	v_add_f32_e32 v19, v27, v21
	v_add_f32_e32 v24, v18, v19
	global_store_dwordx4 v[22:23], v[8:11], off
	s_waitcnt vmcnt(22)
	v_mov_b32_e32 v12, v230
	v_mov_b32_e32 v13, v231
	v_mov_b32_e32 v14, v232
	v_mov_b32_e32 v15, v233
	v_lshlrev_b32_e32 v18, 16, v12
	v_and_b32_e32 v19, 0xffff0000, v12
	v_lshlrev_b32_e32 v12, 16, v13
	v_and_b32_e32 v13, 0xffff0000, v13
	v_lshlrev_b32_e32 v20, 16, v14
	v_and_b32_e32 v21, 0xffff0000, v14
	v_lshlrev_b32_e32 v14, 16, v15
	v_and_b32_e32 v15, 0xffff0000, v15
	v_pk_add_f32 v[6:7], v[6:7], v[12:13]
	v_pk_add_f32 v[4:5], v[4:5], v[18:19]
	v_pk_add_f32 v[12:13], v[2:3], v[14:15]
	v_pk_add_f32 v[14:15], v[0:1], v[20:21]
	v_mul_f32_e32 v0, v5, v5
	v_mul_f32_e32 v1, v7, v7
	v_mul_f32_e32 v2, v15, v15
	v_mul_f32_e32 v3, v13, v13
	v_fmac_f32_e32 v0, v4, v4
	v_fmac_f32_e32 v1, v6, v6
	v_fmac_f32_e32 v2, v14, v14
	v_fmac_f32_e32 v3, v12, v12
	v_add_f32_e32 v0, v0, v1
	v_add_f32_e32 v1, v2, v3
	v_add_f32_e32 v0, v0, v1
	v_add_f32_e32 v0, v24, v0
	ds_bpermute_b32 v1, v120, v0
	v_cvt_pk_bf16_f32 v2, v4, v5
	v_cvt_pk_bf16_f32 v3, v6, v7
	v_cvt_pk_bf16_f32 v4, v14, v15
	v_cvt_pk_bf16_f32 v5, v12, v13
	s_waitcnt lgkmcnt(0)
	v_add_f32_e32 v0, v0, v1
	ds_bpermute_b32 v1, v114, v0
	global_store_dwordx4 v[22:23], v[2:5], off offset:256
	s_and_saveexec_b64 s[46:47], vcc
	s_cbranch_execz .LBB0_1622
	s_waitcnt lgkmcnt(0)
	v_add_f32_e32 v2, v0, v1
	s_lshl_b32 s26, s14, 2
	v_lshlrev_b64 v[0:1], 6, v[16:17]
	s_ashr_i32 s27, s26, 31
	v_lshl_add_u64 v[0:1], s[12:13], 0, v[0:1]
	v_lshl_add_u64 v[0:1], s[26:27], 2, v[0:1]
	s_lshl_b32 s16, s60, 2
	v_lshl_add_u64 v[0:1], v[0:1], 0, s[16:17]
	global_store_dword v[0:1], v2, off
